# H2 + non-temporal hint on P13's f32 output stores only
# baseline (speedup 1.0000x reference)
;     __device__ __forceinline__ const float* in(int i) const { return karg_in(i); }
; __device__ __forceinline__ const float* xrow_ptr(const Ctx& C, int row) { return row < MPROMPT ? C.in(0) + (size_t)row * DM : C.in(1) + (size_t)(row - MPROMPT) * DM; }
; __device__ __forceinline__ v4f ld4_bf16(const bf16* p) { const v2u w = *(const v2u*)p; return (v4f){bf_lo(w.x), bf_hi(w.x), bf_lo(w.y), bf_hi(w.y)}; }
; __device__ __forceinline__ float ssq4(v4f v) { return (v.x * v.x + v.y * v.y) + (v.z * v.z + v.w * v.w); }
; #define FTID const int ftid_ = fresh_tid()
; template <int R, bool BASE_F32, bool OUT_F32>
; __device__ __forceinline__ void rows_res(const Ctx& C, int m0, int stride, int mx, const float* gpost, float scale, int lane) {
;     v4f d[R][4], b[R][4]; int mr[R]; bool ok[R]; float r1[R];
;     const bf16* D = C.D(); bf16* XN = C.XN();
; #pragma unroll
;     for (int r = 0; r < R; ++r) { mr[r] = (r == 4) ? mx : m0 + r * stride; ok[r] = (r == 4) ? (mx < M) : (mr[r] < MPROMPT); const int mm = ok[r] ? mr[r] : 0;
; #pragma unroll
;         for (int j = 0; j < 4; ++j) d[r][j] = ld4_bf16(D + (size_t)mm * DM + 4 * lane + 256 * j);
;         if (BASE_F32) { const float* x = xrow_ptr(C, mm);
; #pragma unroll
;             for (int j = 0; j < 4; ++j) b[r][j] = ld4_f32(x + 4 * lane + 256 * j);
;         } else { const float inv = C.RS()[mm];
; #pragma unroll
;             for (int j = 0; j < 4; ++j) b[r][j] = ld4_bf16(XN + (size_t)mm * DM + 4 * lane + 256 * j) * inv;
;         } }
; #pragma unroll
;     for (int r = 0; r < R; ++r) { float s = 0.f;
; #pragma unroll
;         for (int j = 0; j < 4; ++j) s += ssq4(d[r][j]);
;         r1[r] = s; }
; #pragma unroll
;     for (int r = 0; r < R; ++r) r1[r] = rsqrtf(wave_sum(r1[r]) * (1.f / DM) + EPS) * scale;
; __global__ void __launch_bounds__(NTHREADS, 2) fwd_kernel(Args args) {
;     ...
;     { FTID; const float* gp = C.in(32); { const int gw_ = GWV, ngw_ = NGWV, nit = (MPROMPT + 4 * ngw_ - 1) / (4 * ngw_);
;       for (int it = 0; it < nit - 1; ++it) rows_res<4, false, true>(C, gw_ + 4 * it * ngw_, ngw_, M, gp, 0.5f, LANE);
;       rows_res<5, false, true>(C, gw_ + 4 * (nit - 1) * ngw_, ngw_, MPROMPT + gw_, gp, 0.5f, LANE);
;       for (int ms = MPROMPT + gw_ + ngw_; ms < M; ms += ngw_) rows_res<5, false, true>(C, MPROMPT, ngw_, ms, gp, 0.5f, LANE); } }
.LBB0_1272:
	s_or_b64 exec, exec, s[4:5]
	s_mov_b64 s[0:1], s[80:81]
	s_waitcnt lgkmcnt(0)
	s_barrier
	s_load_dwordx2 s[8:9], s[0:1], 0x100
	v_readfirstlane_b32 s0, v182
	v_lshlrev_b32_e32 v0, 2, v182
	s_ashr_i32 s26, s0, 6
	v_readlane_b32 s0, v232, 0
	v_and_b32_e32 v0, 0xfc, v0
	s_add_i32 s15, s26, s0
	v_mov_b32_e32 v17, 0
	s_and_b64 vcc, exec, s[6:7]
	v_lshlrev_b32_e32 v16, 2, v0
	v_lshlrev_b32_e32 v18, 1, v0
	s_load_dwordx2 s[98:99], s[80:81], 0x110
	s_load_dwordx2 s[100:101], s[80:81], 0x100
	v_and_b32_e32 v176, 63, v182
	v_lshlrev_b32_e32 v170, 3, v176
	s_lshl_b32 vcc_lo, s15, 11
	v_add_u32_e32 v170, vcc_lo, v170
	v_add_u32_e32 v171, 0x3000000, v170
	v_add_u32_e32 v170, 0x7100000, v170
	v_mov_b32_e32 v173, v171
	s_lshl_b32 vcc_lo, s15, 2
	v_mov_b32_e32 v172, 0x2a80000
	v_add_u32_e32 v172, vcc_lo, v172
	v_mov_b32_e32 v174, v172
	s_lshl_b32 vcc_lo, s15, 12
	v_lshlrev_b32_e32 v175, 4, v176
	v_add_u32_e32 v175, vcc_lo, v175
	v_lshlrev_b32_e32 v176, 4, v176
	v_mov_b32_e32 v138, 0x358637bd
	s_waitcnt lgkmcnt(0)
	global_load_dwordx4 v[192:195], v176, s[100:101]
	global_load_dwordx4 v[196:199], v176, s[100:101] offset:1024
	global_load_dwordx4 v[200:203], v176, s[100:101] offset:2048
	global_load_dwordx4 v[204:207], v176, s[100:101] offset:3072
	s_load_dwordx2 s[100:101], s[80:81], 0x108
	global_load_dword v52, v172, s[98:99]
	global_load_dwordx2 v[20:21], v170, s[98:99]
	global_load_dwordx2 v[22:23], v170, s[98:99] offset:512
	global_load_dwordx2 v[24:25], v170, s[98:99] offset:1024
	global_load_dwordx2 v[26:27], v170, s[98:99] offset:1536
	global_load_dwordx2 v[36:37], v171, s[98:99]
	global_load_dwordx2 v[38:39], v171, s[98:99] offset:512
	global_load_dwordx2 v[40:41], v171, s[98:99] offset:1024
	global_load_dwordx2 v[42:43], v171, s[98:99] offset:1536
	v_add_u32_e32 v170, 0x400000, v170
	v_add_u32_e32 v171, 0x400000, v171
	v_add_u32_e32 v172, 0x2000, v172
	global_load_dword v54, v172, s[98:99]
	global_load_dwordx2 v[28:29], v170, s[98:99]
	global_load_dwordx2 v[30:31], v170, s[98:99] offset:512
	global_load_dwordx2 v[32:33], v170, s[98:99] offset:1024
	global_load_dwordx2 v[34:35], v170, s[98:99] offset:1536
	global_load_dwordx2 v[44:45], v171, s[98:99]
	global_load_dwordx2 v[46:47], v171, s[98:99] offset:512
	global_load_dwordx2 v[48:49], v171, s[98:99] offset:1024
	global_load_dwordx2 v[50:51], v171, s[98:99] offset:1536
	v_add_u32_e32 v170, 0x400000, v170
	v_add_u32_e32 v171, 0x400000, v171
	v_add_u32_e32 v172, 0x2000, v172
	global_load_dword v88, v172, s[98:99]
	global_load_dwordx2 v[56:57], v170, s[98:99]
	global_load_dwordx2 v[58:59], v170, s[98:99] offset:512
	global_load_dwordx2 v[60:61], v170, s[98:99] offset:1024
	global_load_dwordx2 v[62:63], v170, s[98:99] offset:1536
	global_load_dwordx2 v[72:73], v171, s[98:99]
	global_load_dwordx2 v[74:75], v171, s[98:99] offset:512
	global_load_dwordx2 v[76:77], v171, s[98:99] offset:1024
	global_load_dwordx2 v[78:79], v171, s[98:99] offset:1536
	v_add_u32_e32 v170, 0x400000, v170
	v_add_u32_e32 v171, 0x400000, v171
	v_add_u32_e32 v172, 0x2000, v172
	global_load_dword v90, v172, s[98:99]
	global_load_dwordx2 v[64:65], v170, s[98:99]
	global_load_dwordx2 v[66:67], v170, s[98:99] offset:512
	global_load_dwordx2 v[68:69], v170, s[98:99] offset:1024
	global_load_dwordx2 v[70:71], v170, s[98:99] offset:1536
	global_load_dwordx2 v[80:81], v171, s[98:99]
	global_load_dwordx2 v[82:83], v171, s[98:99] offset:512
	global_load_dwordx2 v[84:85], v171, s[98:99] offset:1024
	global_load_dwordx2 v[86:87], v171, s[98:99] offset:1536
	v_add_u32_e32 v170, 0x400000, v170
	v_add_u32_e32 v171, 0x400000, v171
	v_add_u32_e32 v172, 0x2000, v172
	s_waitcnt vmcnt(31)
	v_lshlrev_b32_e32 v96, 16, v20
	v_and_b32_e32 v97, 0xffff0000, v20
	v_lshlrev_b32_e32 v98, 16, v21
	v_and_b32_e32 v99, 0xffff0000, v21
	v_lshlrev_b32_e32 v100, 16, v22
	v_and_b32_e32 v101, 0xffff0000, v22
	v_lshlrev_b32_e32 v102, 16, v23
	v_and_b32_e32 v103, 0xffff0000, v23
	v_lshlrev_b32_e32 v104, 16, v24
	v_and_b32_e32 v105, 0xffff0000, v24
	v_lshlrev_b32_e32 v106, 16, v25
	v_and_b32_e32 v107, 0xffff0000, v25
	v_lshlrev_b32_e32 v108, 16, v26
	v_and_b32_e32 v109, 0xffff0000, v26
	v_lshlrev_b32_e32 v110, 16, v27
	v_and_b32_e32 v111, 0xffff0000, v27
	v_pk_mul_f32 v[128:129], v[96:97], v[96:97]
	v_pk_fma_f32 v[128:129], v[98:99], v[98:99], v[128:129]
	v_pk_fma_f32 v[128:129], v[100:101], v[100:101], v[128:129]
	v_pk_fma_f32 v[128:129], v[102:103], v[102:103], v[128:129]
	v_pk_fma_f32 v[128:129], v[104:105], v[104:105], v[128:129]
	v_pk_fma_f32 v[128:129], v[106:107], v[106:107], v[128:129]
	v_pk_fma_f32 v[128:129], v[108:109], v[108:109], v[128:129]
	v_pk_fma_f32 v[128:129], v[110:111], v[110:111], v[128:129]
	s_nop 0
	v_add_f32_e32 v128, v128, v129
	s_waitcnt vmcnt(22)
;     __device__ __forceinline__ float* out() const { return (float*)karg_in(33); }
; __device__ __forceinline__ float ssq4(v4f v) { return (v.x * v.x + v.y * v.y) + (v.z * v.z + v.w * v.w); }
; template <int R, bool BASE_F32, bool OUT_F32>
; __device__ __forceinline__ void rows_res(const Ctx& C, int m0, int stride, int mx, const float* gpost, float scale, int lane) {
;     ...
;     for (int r = 0; r < R; ++r) { float s = 0.f;
; #pragma unroll
;         for (int j = 0; j < 4; ++j) s += ssq4(d[r][j]);
;         r1[r] = s; }
; #pragma unroll
;     for (int r = 0; r < R; ++r) r1[r] = rsqrtf(wave_sum(r1[r]) * (1.f / DM) + EPS) * scale;
; #pragma unroll
;     for (int j = 0; j < 4; ++j) { const v4f gp = ld4_f32(gpost + 4 * lane + 256 * j);
; #pragma unroll
;         for (int r = 0; r < R; ++r) d[r][j] = b[r][j] + d[r][j] * r1[r] * gp; }
;     if (OUT_F32) { float* Y = C.out();
; #pragma unroll
;         for (int r = 0; r < R; ++r)
; #pragma unroll
;             for (int j = 0; j < 4; ++j) if (ok[r]) *(v4f*)(Y + (size_t)mr[r] * DM + 4 * lane + 256 * j) = d[r][j];
	v_lshlrev_b32_e32 v112, 16, v28
	v_and_b32_e32 v113, 0xffff0000, v28
	v_lshlrev_b32_e32 v114, 16, v29
	v_and_b32_e32 v115, 0xffff0000, v29
	v_lshlrev_b32_e32 v116, 16, v30
	v_and_b32_e32 v117, 0xffff0000, v30
	v_lshlrev_b32_e32 v118, 16, v31
	v_and_b32_e32 v119, 0xffff0000, v31
	v_lshlrev_b32_e32 v120, 16, v32
	v_and_b32_e32 v121, 0xffff0000, v32
	v_lshlrev_b32_e32 v122, 16, v33
	v_and_b32_e32 v123, 0xffff0000, v33
	v_lshlrev_b32_e32 v124, 16, v34
	v_and_b32_e32 v125, 0xffff0000, v34
	v_lshlrev_b32_e32 v126, 16, v35
	v_and_b32_e32 v127, 0xffff0000, v35
	v_pk_mul_f32 v[130:131], v[112:113], v[112:113]
	v_pk_fma_f32 v[130:131], v[114:115], v[114:115], v[130:131]
	v_pk_fma_f32 v[130:131], v[116:117], v[116:117], v[130:131]
	v_pk_fma_f32 v[130:131], v[118:119], v[118:119], v[130:131]
	v_pk_fma_f32 v[130:131], v[120:121], v[120:121], v[130:131]
	v_pk_fma_f32 v[130:131], v[122:123], v[122:123], v[130:131]
	v_pk_fma_f32 v[130:131], v[124:125], v[124:125], v[130:131]
	v_pk_fma_f32 v[130:131], v[126:127], v[126:127], v[130:131]
	s_nop 0
	v_add_f32_e32 v130, v130, v131
	s_nop 1
	v_add_f32_dpp v128, v128, v128 quad_perm:[1,0,3,2] row_mask:0xf bank_mask:0xf
	v_add_f32_dpp v130, v130, v130 quad_perm:[1,0,3,2] row_mask:0xf bank_mask:0xf
	s_nop 0
	v_add_f32_dpp v128, v128, v128 quad_perm:[2,3,0,1] row_mask:0xf bank_mask:0xf
	v_add_f32_dpp v130, v130, v130 quad_perm:[2,3,0,1] row_mask:0xf bank_mask:0xf
	s_nop 0
	v_add_f32_dpp v128, v128, v128 row_half_mirror row_mask:0xf bank_mask:0xf
	v_add_f32_dpp v130, v130, v130 row_half_mirror row_mask:0xf bank_mask:0xf
	s_nop 0
	v_add_f32_dpp v128, v128, v128 row_mirror row_mask:0xf bank_mask:0xf
	v_add_f32_dpp v130, v130, v130 row_mirror row_mask:0xf bank_mask:0xf
	s_nop 0
	ds_bpermute_b32 v136, v187, v128
	ds_bpermute_b32 v137, v187, v130
	s_waitcnt lgkmcnt(0)
	v_add_f32_e32 v128, v128, v136
	v_add_f32_e32 v130, v130, v137
	ds_bpermute_b32 v136, v188, v128
	ds_bpermute_b32 v137, v188, v130
	s_waitcnt lgkmcnt(0)
	v_add_f32_e32 v128, v128, v136
	v_add_f32_e32 v130, v130, v137
	v_fmamk_f32 v128, v128, 0x3a800000, v138
	v_fmamk_f32 v130, v130, 0x3a800000, v138
	s_nop 0
	v_rsq_f32_e32 v128, v128
	v_rsq_f32_e32 v130, v130
	s_nop 1
	v_mul_f32_e32 v128, 0.5, v128
	v_mul_f32_e32 v130, 0.5, v130
	s_waitcnt vmcnt(18)
	v_pk_mul_f32 v[96:97], v[128:129], v[96:97] op_sel_hi:[0,1]
	v_pk_mul_f32 v[98:99], v[128:129], v[98:99] op_sel_hi:[0,1]
	v_pk_mul_f32 v[100:101], v[128:129], v[100:101] op_sel_hi:[0,1]
	v_pk_mul_f32 v[102:103], v[128:129], v[102:103] op_sel_hi:[0,1]
	v_pk_mul_f32 v[104:105], v[128:129], v[104:105] op_sel_hi:[0,1]
	v_pk_mul_f32 v[106:107], v[128:129], v[106:107] op_sel_hi:[0,1]
	v_pk_mul_f32 v[108:109], v[128:129], v[108:109] op_sel_hi:[0,1]
	v_pk_mul_f32 v[110:111], v[128:129], v[110:111] op_sel_hi:[0,1]
	v_pk_mul_f32 v[96:97], v[96:97], v[192:193]
	v_pk_mul_f32 v[98:99], v[98:99], v[194:195]
	v_pk_mul_f32 v[100:101], v[100:101], v[196:197]
	v_pk_mul_f32 v[102:103], v[102:103], v[198:199]
	v_pk_mul_f32 v[104:105], v[104:105], v[200:201]
	v_pk_mul_f32 v[106:107], v[106:107], v[202:203]
	v_pk_mul_f32 v[108:109], v[108:109], v[204:205]
	v_pk_mul_f32 v[110:111], v[110:111], v[206:207]
	v_lshlrev_b32_e32 v20, 16, v36
	v_and_b32_e32 v21, 0xffff0000, v36
	v_lshlrev_b32_e32 v22, 16, v37
	v_and_b32_e32 v23, 0xffff0000, v37
	v_lshlrev_b32_e32 v24, 16, v38
	v_and_b32_e32 v25, 0xffff0000, v38
	v_lshlrev_b32_e32 v26, 16, v39
	v_and_b32_e32 v27, 0xffff0000, v39
	v_pk_fma_f32 v[96:97], v[52:53], v[20:21], v[96:97] op_sel_hi:[0,1,1]
	v_pk_fma_f32 v[98:99], v[52:53], v[22:23], v[98:99] op_sel_hi:[0,1,1]
	v_pk_fma_f32 v[100:101], v[52:53], v[24:25], v[100:101] op_sel_hi:[0,1,1]
	v_pk_fma_f32 v[102:103], v[52:53], v[26:27], v[102:103] op_sel_hi:[0,1,1]
	v_lshlrev_b32_e32 v20, 16, v40
	v_and_b32_e32 v21, 0xffff0000, v40
	v_lshlrev_b32_e32 v22, 16, v41
	v_and_b32_e32 v23, 0xffff0000, v41
	v_lshlrev_b32_e32 v24, 16, v42
	v_and_b32_e32 v25, 0xffff0000, v42
	v_lshlrev_b32_e32 v26, 16, v43
	v_and_b32_e32 v27, 0xffff0000, v43
	v_pk_fma_f32 v[104:105], v[52:53], v[20:21], v[104:105] op_sel_hi:[0,1,1]
	v_pk_fma_f32 v[106:107], v[52:53], v[22:23], v[106:107] op_sel_hi:[0,1,1]
	v_pk_fma_f32 v[108:109], v[52:53], v[24:25], v[108:109] op_sel_hi:[0,1,1]
	v_pk_fma_f32 v[110:111], v[52:53], v[26:27], v[110:111] op_sel_hi:[0,1,1]
	global_store_dwordx4 v175, v[96:99], s[100:101] nt
	global_store_dwordx4 v175, v[100:103], s[100:101] offset:1024 nt
	global_store_dwordx4 v175, v[104:107], s[100:101] offset:2048 nt
	global_store_dwordx4 v175, v[108:111], s[100:101] offset:3072 nt
	v_add_u32_e32 v175, 0x800000, v175
	v_pk_mul_f32 v[112:113], v[130:131], v[112:113] op_sel_hi:[0,1]
	v_pk_mul_f32 v[114:115], v[130:131], v[114:115] op_sel_hi:[0,1]
	v_pk_mul_f32 v[116:117], v[130:131], v[116:117] op_sel_hi:[0,1]
	v_pk_mul_f32 v[118:119], v[130:131], v[118:119] op_sel_hi:[0,1]
	v_pk_mul_f32 v[120:121], v[130:131], v[120:121] op_sel_hi:[0,1]
	v_pk_mul_f32 v[122:123], v[130:131], v[122:123] op_sel_hi:[0,1]
	v_pk_mul_f32 v[124:125], v[130:131], v[124:125] op_sel_hi:[0,1]
	v_pk_mul_f32 v[126:127], v[130:131], v[126:127] op_sel_hi:[0,1]
	v_pk_mul_f32 v[112:113], v[112:113], v[192:193]
	v_pk_mul_f32 v[114:115], v[114:115], v[194:195]
	v_pk_mul_f32 v[116:117], v[116:117], v[196:197]
	v_pk_mul_f32 v[118:119], v[118:119], v[198:199]
	v_pk_mul_f32 v[120:121], v[120:121], v[200:201]
	v_pk_mul_f32 v[122:123], v[122:123], v[202:203]
	v_pk_mul_f32 v[124:125], v[124:125], v[204:205]
	v_pk_mul_f32 v[126:127], v[126:127], v[206:207]
	v_lshlrev_b32_e32 v28, 16, v44
	v_and_b32_e32 v29, 0xffff0000, v44
	v_lshlrev_b32_e32 v30, 16, v45
	v_and_b32_e32 v31, 0xffff0000, v45
;     __device__ __forceinline__ float* out() const { return (float*)karg_in(33); }
; __device__ __forceinline__ float ssq4(v4f v) { return (v.x * v.x + v.y * v.y) + (v.z * v.z + v.w * v.w); }
; template <int R, bool BASE_F32, bool OUT_F32>
; __device__ __forceinline__ void rows_res(const Ctx& C, int m0, int stride, int mx, const float* gpost, float scale, int lane) {
;     ...
;     for (int r = 0; r < R; ++r) { float s = 0.f;
; #pragma unroll
;         for (int j = 0; j < 4; ++j) s += ssq4(d[r][j]);
;         r1[r] = s; }
; #pragma unroll
;     for (int r = 0; r < R; ++r) r1[r] = rsqrtf(wave_sum(r1[r]) * (1.f / DM) + EPS) * scale;
; #pragma unroll
;     for (int j = 0; j < 4; ++j) { const v4f gp = ld4_f32(gpost + 4 * lane + 256 * j);
; #pragma unroll
;         for (int r = 0; r < R; ++r) d[r][j] = b[r][j] + d[r][j] * r1[r] * gp; }
;     if (OUT_F32) { float* Y = C.out();
; #pragma unroll
;         for (int r = 0; r < R; ++r)
; #pragma unroll
;             for (int j = 0; j < 4; ++j) if (ok[r]) *(v4f*)(Y + (size_t)mr[r] * DM + 4 * lane + 256 * j) = d[r][j];
	v_lshlrev_b32_e32 v32, 16, v46
	v_and_b32_e32 v33, 0xffff0000, v46
	v_lshlrev_b32_e32 v34, 16, v47
	v_and_b32_e32 v35, 0xffff0000, v47
	v_pk_fma_f32 v[112:113], v[54:55], v[28:29], v[112:113] op_sel_hi:[0,1,1]
	v_pk_fma_f32 v[114:115], v[54:55], v[30:31], v[114:115] op_sel_hi:[0,1,1]
	v_pk_fma_f32 v[116:117], v[54:55], v[32:33], v[116:117] op_sel_hi:[0,1,1]
	v_pk_fma_f32 v[118:119], v[54:55], v[34:35], v[118:119] op_sel_hi:[0,1,1]
	v_lshlrev_b32_e32 v28, 16, v48
	v_and_b32_e32 v29, 0xffff0000, v48
	v_lshlrev_b32_e32 v30, 16, v49
	v_and_b32_e32 v31, 0xffff0000, v49
	v_lshlrev_b32_e32 v32, 16, v50
	v_and_b32_e32 v33, 0xffff0000, v50
	v_lshlrev_b32_e32 v34, 16, v51
	v_and_b32_e32 v35, 0xffff0000, v51
	v_pk_fma_f32 v[120:121], v[54:55], v[28:29], v[120:121] op_sel_hi:[0,1,1]
	v_pk_fma_f32 v[122:123], v[54:55], v[30:31], v[122:123] op_sel_hi:[0,1,1]
	v_pk_fma_f32 v[124:125], v[54:55], v[32:33], v[124:125] op_sel_hi:[0,1,1]
	v_pk_fma_f32 v[126:127], v[54:55], v[34:35], v[126:127] op_sel_hi:[0,1,1]
	global_store_dwordx4 v175, v[112:115], s[100:101] nt
	global_store_dwordx4 v175, v[116:119], s[100:101] offset:1024 nt
	global_store_dwordx4 v175, v[120:123], s[100:101] offset:2048 nt
	global_store_dwordx4 v175, v[124:127], s[100:101] offset:3072 nt
	v_add_u32_e32 v175, 0x800000, v175
	global_load_dword v52, v172, s[98:99]
	global_load_dwordx2 v[20:21], v170, s[98:99]
	global_load_dwordx2 v[22:23], v170, s[98:99] offset:512
	global_load_dwordx2 v[24:25], v170, s[98:99] offset:1024
	global_load_dwordx2 v[26:27], v170, s[98:99] offset:1536
	global_load_dwordx2 v[36:37], v171, s[98:99]
	global_load_dwordx2 v[38:39], v171, s[98:99] offset:512
	global_load_dwordx2 v[40:41], v171, s[98:99] offset:1024
	global_load_dwordx2 v[42:43], v171, s[98:99] offset:1536
	v_add_u32_e32 v170, 0x400000, v170
	v_add_u32_e32 v171, 0x400000, v171
	v_add_u32_e32 v172, 0x2000, v172
	global_load_dword v54, v172, s[98:99]
	global_load_dwordx2 v[28:29], v170, s[98:99]
	global_load_dwordx2 v[30:31], v170, s[98:99] offset:512
	global_load_dwordx2 v[32:33], v170, s[98:99] offset:1024
	global_load_dwordx2 v[34:35], v170, s[98:99] offset:1536
	global_load_dwordx2 v[44:45], v171, s[98:99]
	global_load_dwordx2 v[46:47], v171, s[98:99] offset:512
	global_load_dwordx2 v[48:49], v171, s[98:99] offset:1024
	global_load_dwordx2 v[50:51], v171, s[98:99] offset:1536
	v_add_u32_e32 v170, 0x400000, v170
	v_add_u32_e32 v171, 0x400000, v171
	v_add_u32_e32 v172, 0x2000, v172
	s_waitcnt vmcnt(39)
	v_lshlrev_b32_e32 v96, 16, v56
	v_and_b32_e32 v97, 0xffff0000, v56
	v_lshlrev_b32_e32 v98, 16, v57
	v_and_b32_e32 v99, 0xffff0000, v57
	v_lshlrev_b32_e32 v100, 16, v58
	v_and_b32_e32 v101, 0xffff0000, v58
	v_lshlrev_b32_e32 v102, 16, v59
	v_and_b32_e32 v103, 0xffff0000, v59
	v_lshlrev_b32_e32 v104, 16, v60
	v_and_b32_e32 v105, 0xffff0000, v60
	v_lshlrev_b32_e32 v106, 16, v61
	v_and_b32_e32 v107, 0xffff0000, v61
	v_lshlrev_b32_e32 v108, 16, v62
	v_and_b32_e32 v109, 0xffff0000, v62
	v_lshlrev_b32_e32 v110, 16, v63
	v_and_b32_e32 v111, 0xffff0000, v63
	v_pk_mul_f32 v[128:129], v[96:97], v[96:97]
	v_pk_fma_f32 v[128:129], v[98:99], v[98:99], v[128:129]
	v_pk_fma_f32 v[128:129], v[100:101], v[100:101], v[128:129]
	v_pk_fma_f32 v[128:129], v[102:103], v[102:103], v[128:129]
	v_pk_fma_f32 v[128:129], v[104:105], v[104:105], v[128:129]
	v_pk_fma_f32 v[128:129], v[106:107], v[106:107], v[128:129]
	v_pk_fma_f32 v[128:129], v[108:109], v[108:109], v[128:129]
	v_pk_fma_f32 v[128:129], v[110:111], v[110:111], v[128:129]
	s_nop 0
	v_add_f32_e32 v128, v128, v129
	s_waitcnt vmcnt(30)
	v_lshlrev_b32_e32 v112, 16, v64
	v_and_b32_e32 v113, 0xffff0000, v64
	v_lshlrev_b32_e32 v114, 16, v65
	v_and_b32_e32 v115, 0xffff0000, v65
	v_lshlrev_b32_e32 v116, 16, v66
	v_and_b32_e32 v117, 0xffff0000, v66
	v_lshlrev_b32_e32 v118, 16, v67
	v_and_b32_e32 v119, 0xffff0000, v67
	v_lshlrev_b32_e32 v120, 16, v68
	v_and_b32_e32 v121, 0xffff0000, v68
	v_lshlrev_b32_e32 v122, 16, v69
	v_and_b32_e32 v123, 0xffff0000, v69
	v_lshlrev_b32_e32 v124, 16, v70
	v_and_b32_e32 v125, 0xffff0000, v70
	v_lshlrev_b32_e32 v126, 16, v71
	v_and_b32_e32 v127, 0xffff0000, v71
	v_pk_mul_f32 v[130:131], v[112:113], v[112:113]
	v_pk_fma_f32 v[130:131], v[114:115], v[114:115], v[130:131]
	v_pk_fma_f32 v[130:131], v[116:117], v[116:117], v[130:131]
	v_pk_fma_f32 v[130:131], v[118:119], v[118:119], v[130:131]
	v_pk_fma_f32 v[130:131], v[120:121], v[120:121], v[130:131]
	v_pk_fma_f32 v[130:131], v[122:123], v[122:123], v[130:131]
	v_pk_fma_f32 v[130:131], v[124:125], v[124:125], v[130:131]
	v_pk_fma_f32 v[130:131], v[126:127], v[126:127], v[130:131]
	s_nop 0
	v_add_f32_e32 v130, v130, v131
	s_nop 1
	v_add_f32_dpp v128, v128, v128 quad_perm:[1,0,3,2] row_mask:0xf bank_mask:0xf
	v_add_f32_dpp v130, v130, v130 quad_perm:[1,0,3,2] row_mask:0xf bank_mask:0xf
	s_nop 0
	v_add_f32_dpp v128, v128, v128 quad_perm:[2,3,0,1] row_mask:0xf bank_mask:0xf
	v_add_f32_dpp v130, v130, v130 quad_perm:[2,3,0,1] row_mask:0xf bank_mask:0xf
	s_nop 0
	v_add_f32_dpp v128, v128, v128 row_half_mirror row_mask:0xf bank_mask:0xf
	v_add_f32_dpp v130, v130, v130 row_half_mirror row_mask:0xf bank_mask:0xf
	s_nop 0
	v_add_f32_dpp v128, v128, v128 row_mirror row_mask:0xf bank_mask:0xf
	v_add_f32_dpp v130, v130, v130 row_mirror row_mask:0xf bank_mask:0xf
	s_nop 0
	ds_bpermute_b32 v136, v187, v128
	ds_bpermute_b32 v137, v187, v130
	s_waitcnt lgkmcnt(0)
	v_add_f32_e32 v128, v128, v136
	v_add_f32_e32 v130, v130, v137
	ds_bpermute_b32 v136, v188, v128
	ds_bpermute_b32 v137, v188, v130
	s_waitcnt lgkmcnt(0)
;     __device__ __forceinline__ float* out() const { return (float*)karg_in(33); }
; __device__ __forceinline__ float ssq4(v4f v) { return (v.x * v.x + v.y * v.y) + (v.z * v.z + v.w * v.w); }
; template <int R, bool BASE_F32, bool OUT_F32>
; __device__ __forceinline__ void rows_res(const Ctx& C, int m0, int stride, int mx, const float* gpost, float scale, int lane) {
;     ...
;     for (int r = 0; r < R; ++r) { float s = 0.f;
; #pragma unroll
;         for (int j = 0; j < 4; ++j) s += ssq4(d[r][j]);
;         r1[r] = s; }
; #pragma unroll
;     for (int r = 0; r < R; ++r) r1[r] = rsqrtf(wave_sum(r1[r]) * (1.f / DM) + EPS) * scale;
; #pragma unroll
;     for (int j = 0; j < 4; ++j) { const v4f gp = ld4_f32(gpost + 4 * lane + 256 * j);
; #pragma unroll
;         for (int r = 0; r < R; ++r) d[r][j] = b[r][j] + d[r][j] * r1[r] * gp; }
;     if (OUT_F32) { float* Y = C.out();
; #pragma unroll
;         for (int r = 0; r < R; ++r)
; #pragma unroll
;             for (int j = 0; j < 4; ++j) if (ok[r]) *(v4f*)(Y + (size_t)mr[r] * DM + 4 * lane + 256 * j) = d[r][j];
	v_add_f32_e32 v128, v128, v136
	v_add_f32_e32 v130, v130, v137
	v_fmamk_f32 v128, v128, 0x3a800000, v138
	v_fmamk_f32 v130, v130, 0x3a800000, v138
	s_nop 0
	v_rsq_f32_e32 v128, v128
	v_rsq_f32_e32 v130, v130
	s_nop 1
	v_mul_f32_e32 v128, 0.5, v128
	v_mul_f32_e32 v130, 0.5, v130
	s_waitcnt vmcnt(26)
	v_pk_mul_f32 v[96:97], v[128:129], v[96:97] op_sel_hi:[0,1]
	v_pk_mul_f32 v[98:99], v[128:129], v[98:99] op_sel_hi:[0,1]
	v_pk_mul_f32 v[100:101], v[128:129], v[100:101] op_sel_hi:[0,1]
	v_pk_mul_f32 v[102:103], v[128:129], v[102:103] op_sel_hi:[0,1]
	v_pk_mul_f32 v[104:105], v[128:129], v[104:105] op_sel_hi:[0,1]
	v_pk_mul_f32 v[106:107], v[128:129], v[106:107] op_sel_hi:[0,1]
	v_pk_mul_f32 v[108:109], v[128:129], v[108:109] op_sel_hi:[0,1]
	v_pk_mul_f32 v[110:111], v[128:129], v[110:111] op_sel_hi:[0,1]
	v_pk_mul_f32 v[96:97], v[96:97], v[192:193]
	v_pk_mul_f32 v[98:99], v[98:99], v[194:195]
	v_pk_mul_f32 v[100:101], v[100:101], v[196:197]
	v_pk_mul_f32 v[102:103], v[102:103], v[198:199]
	v_pk_mul_f32 v[104:105], v[104:105], v[200:201]
	v_pk_mul_f32 v[106:107], v[106:107], v[202:203]
	v_pk_mul_f32 v[108:109], v[108:109], v[204:205]
	v_pk_mul_f32 v[110:111], v[110:111], v[206:207]
	v_lshlrev_b32_e32 v56, 16, v72
	v_and_b32_e32 v57, 0xffff0000, v72
	v_lshlrev_b32_e32 v58, 16, v73
	v_and_b32_e32 v59, 0xffff0000, v73
	v_lshlrev_b32_e32 v60, 16, v74
	v_and_b32_e32 v61, 0xffff0000, v74
	v_lshlrev_b32_e32 v62, 16, v75
	v_and_b32_e32 v63, 0xffff0000, v75
	v_pk_fma_f32 v[96:97], v[88:89], v[56:57], v[96:97] op_sel_hi:[0,1,1]
	v_pk_fma_f32 v[98:99], v[88:89], v[58:59], v[98:99] op_sel_hi:[0,1,1]
	v_pk_fma_f32 v[100:101], v[88:89], v[60:61], v[100:101] op_sel_hi:[0,1,1]
	v_pk_fma_f32 v[102:103], v[88:89], v[62:63], v[102:103] op_sel_hi:[0,1,1]
	v_lshlrev_b32_e32 v56, 16, v76
	v_and_b32_e32 v57, 0xffff0000, v76
	v_lshlrev_b32_e32 v58, 16, v77
	v_and_b32_e32 v59, 0xffff0000, v77
	v_lshlrev_b32_e32 v60, 16, v78
	v_and_b32_e32 v61, 0xffff0000, v78
	v_lshlrev_b32_e32 v62, 16, v79
	v_and_b32_e32 v63, 0xffff0000, v79
	v_pk_fma_f32 v[104:105], v[88:89], v[56:57], v[104:105] op_sel_hi:[0,1,1]
	v_pk_fma_f32 v[106:107], v[88:89], v[58:59], v[106:107] op_sel_hi:[0,1,1]
	v_pk_fma_f32 v[108:109], v[88:89], v[60:61], v[108:109] op_sel_hi:[0,1,1]
	v_pk_fma_f32 v[110:111], v[88:89], v[62:63], v[110:111] op_sel_hi:[0,1,1]
	global_store_dwordx4 v175, v[96:99], s[100:101] nt
	global_store_dwordx4 v175, v[100:103], s[100:101] offset:1024 nt
	global_store_dwordx4 v175, v[104:107], s[100:101] offset:2048 nt
	global_store_dwordx4 v175, v[108:111], s[100:101] offset:3072 nt
	v_add_u32_e32 v175, 0x800000, v175
	v_pk_mul_f32 v[112:113], v[130:131], v[112:113] op_sel_hi:[0,1]
	v_pk_mul_f32 v[114:115], v[130:131], v[114:115] op_sel_hi:[0,1]
	v_pk_mul_f32 v[116:117], v[130:131], v[116:117] op_sel_hi:[0,1]
	v_pk_mul_f32 v[118:119], v[130:131], v[118:119] op_sel_hi:[0,1]
	v_pk_mul_f32 v[120:121], v[130:131], v[120:121] op_sel_hi:[0,1]
	v_pk_mul_f32 v[122:123], v[130:131], v[122:123] op_sel_hi:[0,1]
	v_pk_mul_f32 v[124:125], v[130:131], v[124:125] op_sel_hi:[0,1]
	v_pk_mul_f32 v[126:127], v[130:131], v[126:127] op_sel_hi:[0,1]
	v_pk_mul_f32 v[112:113], v[112:113], v[192:193]
	v_pk_mul_f32 v[114:115], v[114:115], v[194:195]
	v_pk_mul_f32 v[116:117], v[116:117], v[196:197]
	v_pk_mul_f32 v[118:119], v[118:119], v[198:199]
	v_pk_mul_f32 v[120:121], v[120:121], v[200:201]
	v_pk_mul_f32 v[122:123], v[122:123], v[202:203]
	v_pk_mul_f32 v[124:125], v[124:125], v[204:205]
	v_pk_mul_f32 v[126:127], v[126:127], v[206:207]
	v_lshlrev_b32_e32 v64, 16, v80
	v_and_b32_e32 v65, 0xffff0000, v80
	v_lshlrev_b32_e32 v66, 16, v81
	v_and_b32_e32 v67, 0xffff0000, v81
	v_lshlrev_b32_e32 v68, 16, v82
	v_and_b32_e32 v69, 0xffff0000, v82
	v_lshlrev_b32_e32 v70, 16, v83
	v_and_b32_e32 v71, 0xffff0000, v83
	v_pk_fma_f32 v[112:113], v[90:91], v[64:65], v[112:113] op_sel_hi:[0,1,1]
	v_pk_fma_f32 v[114:115], v[90:91], v[66:67], v[114:115] op_sel_hi:[0,1,1]
	v_pk_fma_f32 v[116:117], v[90:91], v[68:69], v[116:117] op_sel_hi:[0,1,1]
	v_pk_fma_f32 v[118:119], v[90:91], v[70:71], v[118:119] op_sel_hi:[0,1,1]
	v_lshlrev_b32_e32 v64, 16, v84
	v_and_b32_e32 v65, 0xffff0000, v84
	v_lshlrev_b32_e32 v66, 16, v85
	v_and_b32_e32 v67, 0xffff0000, v85
	v_lshlrev_b32_e32 v68, 16, v86
	v_and_b32_e32 v69, 0xffff0000, v86
	v_lshlrev_b32_e32 v70, 16, v87
	v_and_b32_e32 v71, 0xffff0000, v87
	v_pk_fma_f32 v[120:121], v[90:91], v[64:65], v[120:121] op_sel_hi:[0,1,1]
	v_pk_fma_f32 v[122:123], v[90:91], v[66:67], v[122:123] op_sel_hi:[0,1,1]
	v_pk_fma_f32 v[124:125], v[90:91], v[68:69], v[124:125] op_sel_hi:[0,1,1]
	v_pk_fma_f32 v[126:127], v[90:91], v[70:71], v[126:127] op_sel_hi:[0,1,1]
	global_store_dwordx4 v175, v[112:115], s[100:101] nt
	global_store_dwordx4 v175, v[116:119], s[100:101] offset:1024 nt
	global_store_dwordx4 v175, v[120:123], s[100:101] offset:2048 nt
	global_store_dwordx4 v175, v[124:127], s[100:101] offset:3072 nt
	v_add_u32_e32 v175, 0x800000, v175
	global_load_dword v88, v172, s[98:99]
	global_load_dwordx2 v[56:57], v170, s[98:99]
	global_load_dwordx2 v[58:59], v170, s[98:99] offset:512
	global_load_dwordx2 v[60:61], v170, s[98:99] offset:1024
	global_load_dwordx2 v[62:63], v170, s[98:99] offset:1536
	global_load_dwordx2 v[72:73], v171, s[98:99]
	global_load_dwordx2 v[74:75], v171, s[98:99] offset:512
	global_load_dwordx2 v[76:77], v171, s[98:99] offset:1024
	global_load_dwordx2 v[78:79], v171, s[98:99] offset:1536
	v_add_u32_e32 v170, 0x400000, v170
	v_add_u32_e32 v171, 0x400000, v171
	v_add_u32_e32 v172, 0x2000, v172
	global_load_dword v90, v172, s[98:99]
	global_load_dwordx2 v[64:65], v170, s[98:99]
	global_load_dwordx2 v[66:67], v170, s[98:99] offset:512
	global_load_dwordx2 v[68:69], v170, s[98:99] offset:1024
	global_load_dwordx2 v[70:71], v170, s[98:99] offset:1536
	global_load_dwordx2 v[80:81], v171, s[98:99]
	global_load_dwordx2 v[82:83], v171, s[98:99] offset:512
	global_load_dwordx2 v[84:85], v171, s[98:99] offset:1024
	global_load_dwordx2 v[86:87], v171, s[98:99] offset:1536
	v_add_u32_e32 v170, 0x400000, v170
	v_add_u32_e32 v171, 0x400000, v171
	v_add_u32_e32 v172, 0x2000, v172
	s_waitcnt vmcnt(39)
;     __device__ __forceinline__ float* out() const { return (float*)karg_in(33); }
; __device__ __forceinline__ float ssq4(v4f v) { return (v.x * v.x + v.y * v.y) + (v.z * v.z + v.w * v.w); }
; template <int R, bool BASE_F32, bool OUT_F32>
; __device__ __forceinline__ void rows_res(const Ctx& C, int m0, int stride, int mx, const float* gpost, float scale, int lane) {
;     ...
;     for (int r = 0; r < R; ++r) { float s = 0.f;
; #pragma unroll
;         for (int j = 0; j < 4; ++j) s += ssq4(d[r][j]);
;         r1[r] = s; }
; #pragma unroll
;     for (int r = 0; r < R; ++r) r1[r] = rsqrtf(wave_sum(r1[r]) * (1.f / DM) + EPS) * scale;
; #pragma unroll
;     for (int j = 0; j < 4; ++j) { const v4f gp = ld4_f32(gpost + 4 * lane + 256 * j);
; #pragma unroll
;         for (int r = 0; r < R; ++r) d[r][j] = b[r][j] + d[r][j] * r1[r] * gp; }
;     if (OUT_F32) { float* Y = C.out();
; #pragma unroll
;         for (int r = 0; r < R; ++r)
; #pragma unroll
;             for (int j = 0; j < 4; ++j) if (ok[r]) *(v4f*)(Y + (size_t)mr[r] * DM + 4 * lane + 256 * j) = d[r][j];
	v_lshlrev_b32_e32 v96, 16, v20
	v_and_b32_e32 v97, 0xffff0000, v20
	v_lshlrev_b32_e32 v98, 16, v21
	v_and_b32_e32 v99, 0xffff0000, v21
	v_lshlrev_b32_e32 v100, 16, v22
	v_and_b32_e32 v101, 0xffff0000, v22
	v_lshlrev_b32_e32 v102, 16, v23
	v_and_b32_e32 v103, 0xffff0000, v23
	v_lshlrev_b32_e32 v104, 16, v24
	v_and_b32_e32 v105, 0xffff0000, v24
	v_lshlrev_b32_e32 v106, 16, v25
	v_and_b32_e32 v107, 0xffff0000, v25
	v_lshlrev_b32_e32 v108, 16, v26
	v_and_b32_e32 v109, 0xffff0000, v26
	v_lshlrev_b32_e32 v110, 16, v27
	v_and_b32_e32 v111, 0xffff0000, v27
	v_pk_mul_f32 v[128:129], v[96:97], v[96:97]
	v_pk_fma_f32 v[128:129], v[98:99], v[98:99], v[128:129]
	v_pk_fma_f32 v[128:129], v[100:101], v[100:101], v[128:129]
	v_pk_fma_f32 v[128:129], v[102:103], v[102:103], v[128:129]
	v_pk_fma_f32 v[128:129], v[104:105], v[104:105], v[128:129]
	v_pk_fma_f32 v[128:129], v[106:107], v[106:107], v[128:129]
	v_pk_fma_f32 v[128:129], v[108:109], v[108:109], v[128:129]
	v_pk_fma_f32 v[128:129], v[110:111], v[110:111], v[128:129]
	s_nop 0
	v_add_f32_e32 v128, v128, v129
	s_waitcnt vmcnt(30)
	v_lshlrev_b32_e32 v112, 16, v28
	v_and_b32_e32 v113, 0xffff0000, v28
	v_lshlrev_b32_e32 v114, 16, v29
	v_and_b32_e32 v115, 0xffff0000, v29
	v_lshlrev_b32_e32 v116, 16, v30
	v_and_b32_e32 v117, 0xffff0000, v30
	v_lshlrev_b32_e32 v118, 16, v31
	v_and_b32_e32 v119, 0xffff0000, v31
	v_lshlrev_b32_e32 v120, 16, v32
	v_and_b32_e32 v121, 0xffff0000, v32
	v_lshlrev_b32_e32 v122, 16, v33
	v_and_b32_e32 v123, 0xffff0000, v33
	v_lshlrev_b32_e32 v124, 16, v34
	v_and_b32_e32 v125, 0xffff0000, v34
	v_lshlrev_b32_e32 v126, 16, v35
	v_and_b32_e32 v127, 0xffff0000, v35
	v_pk_mul_f32 v[130:131], v[112:113], v[112:113]
	v_pk_fma_f32 v[130:131], v[114:115], v[114:115], v[130:131]
	v_pk_fma_f32 v[130:131], v[116:117], v[116:117], v[130:131]
	v_pk_fma_f32 v[130:131], v[118:119], v[118:119], v[130:131]
	v_pk_fma_f32 v[130:131], v[120:121], v[120:121], v[130:131]
	v_pk_fma_f32 v[130:131], v[122:123], v[122:123], v[130:131]
	v_pk_fma_f32 v[130:131], v[124:125], v[124:125], v[130:131]
	v_pk_fma_f32 v[130:131], v[126:127], v[126:127], v[130:131]
	s_nop 0
	v_add_f32_e32 v130, v130, v131
	s_nop 1
	v_add_f32_dpp v128, v128, v128 quad_perm:[1,0,3,2] row_mask:0xf bank_mask:0xf
	v_add_f32_dpp v130, v130, v130 quad_perm:[1,0,3,2] row_mask:0xf bank_mask:0xf
	s_nop 0
	v_add_f32_dpp v128, v128, v128 quad_perm:[2,3,0,1] row_mask:0xf bank_mask:0xf
	v_add_f32_dpp v130, v130, v130 quad_perm:[2,3,0,1] row_mask:0xf bank_mask:0xf
	s_nop 0
	v_add_f32_dpp v128, v128, v128 row_half_mirror row_mask:0xf bank_mask:0xf
	v_add_f32_dpp v130, v130, v130 row_half_mirror row_mask:0xf bank_mask:0xf
	s_nop 0
	v_add_f32_dpp v128, v128, v128 row_mirror row_mask:0xf bank_mask:0xf
	v_add_f32_dpp v130, v130, v130 row_mirror row_mask:0xf bank_mask:0xf
	s_nop 0
	ds_bpermute_b32 v136, v187, v128
	ds_bpermute_b32 v137, v187, v130
	s_waitcnt lgkmcnt(0)
	v_add_f32_e32 v128, v128, v136
	v_add_f32_e32 v130, v130, v137
	ds_bpermute_b32 v136, v188, v128
	ds_bpermute_b32 v137, v188, v130
	s_waitcnt lgkmcnt(0)
	v_add_f32_e32 v128, v128, v136
	v_add_f32_e32 v130, v130, v137
	v_fmamk_f32 v128, v128, 0x3a800000, v138
	v_fmamk_f32 v130, v130, 0x3a800000, v138
	s_nop 0
	v_rsq_f32_e32 v128, v128
	v_rsq_f32_e32 v130, v130
	s_nop 1
	v_mul_f32_e32 v128, 0.5, v128
	v_mul_f32_e32 v130, 0.5, v130
	s_waitcnt vmcnt(26)
	v_pk_mul_f32 v[96:97], v[128:129], v[96:97] op_sel_hi:[0,1]
	v_pk_mul_f32 v[98:99], v[128:129], v[98:99] op_sel_hi:[0,1]
	v_pk_mul_f32 v[100:101], v[128:129], v[100:101] op_sel_hi:[0,1]
	v_pk_mul_f32 v[102:103], v[128:129], v[102:103] op_sel_hi:[0,1]
	v_pk_mul_f32 v[104:105], v[128:129], v[104:105] op_sel_hi:[0,1]
	v_pk_mul_f32 v[106:107], v[128:129], v[106:107] op_sel_hi:[0,1]
	v_pk_mul_f32 v[108:109], v[128:129], v[108:109] op_sel_hi:[0,1]
	v_pk_mul_f32 v[110:111], v[128:129], v[110:111] op_sel_hi:[0,1]
	v_pk_mul_f32 v[96:97], v[96:97], v[192:193]
	v_pk_mul_f32 v[98:99], v[98:99], v[194:195]
	v_pk_mul_f32 v[100:101], v[100:101], v[196:197]
	v_pk_mul_f32 v[102:103], v[102:103], v[198:199]
	v_pk_mul_f32 v[104:105], v[104:105], v[200:201]
	v_pk_mul_f32 v[106:107], v[106:107], v[202:203]
	v_pk_mul_f32 v[108:109], v[108:109], v[204:205]
	v_pk_mul_f32 v[110:111], v[110:111], v[206:207]
	v_lshlrev_b32_e32 v20, 16, v36
	v_and_b32_e32 v21, 0xffff0000, v36
	v_lshlrev_b32_e32 v22, 16, v37
	v_and_b32_e32 v23, 0xffff0000, v37
	v_lshlrev_b32_e32 v24, 16, v38
	v_and_b32_e32 v25, 0xffff0000, v38
	v_lshlrev_b32_e32 v26, 16, v39
	v_and_b32_e32 v27, 0xffff0000, v39
	v_pk_fma_f32 v[96:97], v[52:53], v[20:21], v[96:97] op_sel_hi:[0,1,1]
	v_pk_fma_f32 v[98:99], v[52:53], v[22:23], v[98:99] op_sel_hi:[0,1,1]
	v_pk_fma_f32 v[100:101], v[52:53], v[24:25], v[100:101] op_sel_hi:[0,1,1]
	v_pk_fma_f32 v[102:103], v[52:53], v[26:27], v[102:103] op_sel_hi:[0,1,1]
	v_lshlrev_b32_e32 v20, 16, v40
	v_and_b32_e32 v21, 0xffff0000, v40
	v_lshlrev_b32_e32 v22, 16, v41
	v_and_b32_e32 v23, 0xffff0000, v41
	v_lshlrev_b32_e32 v24, 16, v42
	v_and_b32_e32 v25, 0xffff0000, v42
	v_lshlrev_b32_e32 v26, 16, v43
	v_and_b32_e32 v27, 0xffff0000, v43
	v_pk_fma_f32 v[104:105], v[52:53], v[20:21], v[104:105] op_sel_hi:[0,1,1]
	v_pk_fma_f32 v[106:107], v[52:53], v[22:23], v[106:107] op_sel_hi:[0,1,1]
	v_pk_fma_f32 v[108:109], v[52:53], v[24:25], v[108:109] op_sel_hi:[0,1,1]
	v_pk_fma_f32 v[110:111], v[52:53], v[26:27], v[110:111] op_sel_hi:[0,1,1]
	global_store_dwordx4 v175, v[96:99], s[100:101] nt
	global_store_dwordx4 v175, v[100:103], s[100:101] offset:1024 nt
	global_store_dwordx4 v175, v[104:107], s[100:101] offset:2048 nt
	global_store_dwordx4 v175, v[108:111], s[100:101] offset:3072 nt
;     __device__ __forceinline__ float* out() const { return (float*)karg_in(33); }
; __device__ __forceinline__ float ssq4(v4f v) { return (v.x * v.x + v.y * v.y) + (v.z * v.z + v.w * v.w); }
; template <int R, bool BASE_F32, bool OUT_F32>
; __device__ __forceinline__ void rows_res(const Ctx& C, int m0, int stride, int mx, const float* gpost, float scale, int lane) {
;     ...
;     for (int r = 0; r < R; ++r) { float s = 0.f;
; #pragma unroll
;         for (int j = 0; j < 4; ++j) s += ssq4(d[r][j]);
;         r1[r] = s; }
; #pragma unroll
;     for (int r = 0; r < R; ++r) r1[r] = rsqrtf(wave_sum(r1[r]) * (1.f / DM) + EPS) * scale;
; #pragma unroll
;     for (int j = 0; j < 4; ++j) { const v4f gp = ld4_f32(gpost + 4 * lane + 256 * j);
; #pragma unroll
;         for (int r = 0; r < R; ++r) d[r][j] = b[r][j] + d[r][j] * r1[r] * gp; }
;     if (OUT_F32) { float* Y = C.out();
; #pragma unroll
;         for (int r = 0; r < R; ++r)
; #pragma unroll
;             for (int j = 0; j < 4; ++j) if (ok[r]) *(v4f*)(Y + (size_t)mr[r] * DM + 4 * lane + 256 * j) = d[r][j];
	v_add_u32_e32 v175, 0x800000, v175
	v_pk_mul_f32 v[112:113], v[130:131], v[112:113] op_sel_hi:[0,1]
	v_pk_mul_f32 v[114:115], v[130:131], v[114:115] op_sel_hi:[0,1]
	v_pk_mul_f32 v[116:117], v[130:131], v[116:117] op_sel_hi:[0,1]
	v_pk_mul_f32 v[118:119], v[130:131], v[118:119] op_sel_hi:[0,1]
	v_pk_mul_f32 v[120:121], v[130:131], v[120:121] op_sel_hi:[0,1]
	v_pk_mul_f32 v[122:123], v[130:131], v[122:123] op_sel_hi:[0,1]
	v_pk_mul_f32 v[124:125], v[130:131], v[124:125] op_sel_hi:[0,1]
	v_pk_mul_f32 v[126:127], v[130:131], v[126:127] op_sel_hi:[0,1]
	v_pk_mul_f32 v[112:113], v[112:113], v[192:193]
	v_pk_mul_f32 v[114:115], v[114:115], v[194:195]
	v_pk_mul_f32 v[116:117], v[116:117], v[196:197]
	v_pk_mul_f32 v[118:119], v[118:119], v[198:199]
	v_pk_mul_f32 v[120:121], v[120:121], v[200:201]
	v_pk_mul_f32 v[122:123], v[122:123], v[202:203]
	v_pk_mul_f32 v[124:125], v[124:125], v[204:205]
	v_pk_mul_f32 v[126:127], v[126:127], v[206:207]
	v_lshlrev_b32_e32 v28, 16, v44
	v_and_b32_e32 v29, 0xffff0000, v44
	v_lshlrev_b32_e32 v30, 16, v45
	v_and_b32_e32 v31, 0xffff0000, v45
	v_lshlrev_b32_e32 v32, 16, v46
	v_and_b32_e32 v33, 0xffff0000, v46
	v_lshlrev_b32_e32 v34, 16, v47
	v_and_b32_e32 v35, 0xffff0000, v47
	v_pk_fma_f32 v[112:113], v[54:55], v[28:29], v[112:113] op_sel_hi:[0,1,1]
	v_pk_fma_f32 v[114:115], v[54:55], v[30:31], v[114:115] op_sel_hi:[0,1,1]
	v_pk_fma_f32 v[116:117], v[54:55], v[32:33], v[116:117] op_sel_hi:[0,1,1]
	v_pk_fma_f32 v[118:119], v[54:55], v[34:35], v[118:119] op_sel_hi:[0,1,1]
	v_lshlrev_b32_e32 v28, 16, v48
	v_and_b32_e32 v29, 0xffff0000, v48
	v_lshlrev_b32_e32 v30, 16, v49
	v_and_b32_e32 v31, 0xffff0000, v49
	v_lshlrev_b32_e32 v32, 16, v50
	v_and_b32_e32 v33, 0xffff0000, v50
	v_lshlrev_b32_e32 v34, 16, v51
	v_and_b32_e32 v35, 0xffff0000, v51
	v_pk_fma_f32 v[120:121], v[54:55], v[28:29], v[120:121] op_sel_hi:[0,1,1]
	v_pk_fma_f32 v[122:123], v[54:55], v[30:31], v[122:123] op_sel_hi:[0,1,1]
	v_pk_fma_f32 v[124:125], v[54:55], v[32:33], v[124:125] op_sel_hi:[0,1,1]
	v_pk_fma_f32 v[126:127], v[54:55], v[34:35], v[126:127] op_sel_hi:[0,1,1]
	global_store_dwordx4 v175, v[112:115], s[100:101] nt
	global_store_dwordx4 v175, v[116:119], s[100:101] offset:1024 nt
	global_store_dwordx4 v175, v[120:123], s[100:101] offset:2048 nt
	global_store_dwordx4 v175, v[124:127], s[100:101] offset:3072 nt
	v_add_u32_e32 v175, 0x800000, v175
	global_load_dword v52, v172, s[98:99]
	global_load_dwordx2 v[20:21], v170, s[98:99]
	global_load_dwordx2 v[22:23], v170, s[98:99] offset:512
	global_load_dwordx2 v[24:25], v170, s[98:99] offset:1024
	global_load_dwordx2 v[26:27], v170, s[98:99] offset:1536
	global_load_dwordx2 v[36:37], v171, s[98:99]
	global_load_dwordx2 v[38:39], v171, s[98:99] offset:512
	global_load_dwordx2 v[40:41], v171, s[98:99] offset:1024
	global_load_dwordx2 v[42:43], v171, s[98:99] offset:1536
	v_add_u32_e32 v170, 0x400000, v170
	v_add_u32_e32 v171, 0x400000, v171
	v_add_u32_e32 v172, 0x2000, v172
	global_load_dword v54, v172, s[98:99]
	global_load_dwordx2 v[28:29], v170, s[98:99]
	global_load_dwordx2 v[30:31], v170, s[98:99] offset:512
	global_load_dwordx2 v[32:33], v170, s[98:99] offset:1024
	global_load_dwordx2 v[34:35], v170, s[98:99] offset:1536
	global_load_dwordx2 v[44:45], v171, s[98:99]
	global_load_dwordx2 v[46:47], v171, s[98:99] offset:512
	global_load_dwordx2 v[48:49], v171, s[98:99] offset:1024
	global_load_dwordx2 v[50:51], v171, s[98:99] offset:1536
	v_add_u32_e32 v170, 0x400000, v170
	v_add_u32_e32 v171, 0x400000, v171
	v_add_u32_e32 v172, 0x2000, v172
	s_waitcnt vmcnt(39)
	v_lshlrev_b32_e32 v96, 16, v56
	v_and_b32_e32 v97, 0xffff0000, v56
	v_lshlrev_b32_e32 v98, 16, v57
	v_and_b32_e32 v99, 0xffff0000, v57
	v_lshlrev_b32_e32 v100, 16, v58
	v_and_b32_e32 v101, 0xffff0000, v58
	v_lshlrev_b32_e32 v102, 16, v59
	v_and_b32_e32 v103, 0xffff0000, v59
	v_lshlrev_b32_e32 v104, 16, v60
	v_and_b32_e32 v105, 0xffff0000, v60
	v_lshlrev_b32_e32 v106, 16, v61
	v_and_b32_e32 v107, 0xffff0000, v61
	v_lshlrev_b32_e32 v108, 16, v62
	v_and_b32_e32 v109, 0xffff0000, v62
	v_lshlrev_b32_e32 v110, 16, v63
	v_and_b32_e32 v111, 0xffff0000, v63
	v_pk_mul_f32 v[128:129], v[96:97], v[96:97]
	v_pk_fma_f32 v[128:129], v[98:99], v[98:99], v[128:129]
	v_pk_fma_f32 v[128:129], v[100:101], v[100:101], v[128:129]
	v_pk_fma_f32 v[128:129], v[102:103], v[102:103], v[128:129]
	v_pk_fma_f32 v[128:129], v[104:105], v[104:105], v[128:129]
	v_pk_fma_f32 v[128:129], v[106:107], v[106:107], v[128:129]
	v_pk_fma_f32 v[128:129], v[108:109], v[108:109], v[128:129]
	v_pk_fma_f32 v[128:129], v[110:111], v[110:111], v[128:129]
	s_nop 0
	v_add_f32_e32 v128, v128, v129
	s_waitcnt vmcnt(30)
	v_lshlrev_b32_e32 v112, 16, v64
	v_and_b32_e32 v113, 0xffff0000, v64
	v_lshlrev_b32_e32 v114, 16, v65
	v_and_b32_e32 v115, 0xffff0000, v65
	v_lshlrev_b32_e32 v116, 16, v66
	v_and_b32_e32 v117, 0xffff0000, v66
	v_lshlrev_b32_e32 v118, 16, v67
	v_and_b32_e32 v119, 0xffff0000, v67
	v_lshlrev_b32_e32 v120, 16, v68
	v_and_b32_e32 v121, 0xffff0000, v68
	v_lshlrev_b32_e32 v122, 16, v69
	v_and_b32_e32 v123, 0xffff0000, v69
	v_lshlrev_b32_e32 v124, 16, v70
	v_and_b32_e32 v125, 0xffff0000, v70
	v_lshlrev_b32_e32 v126, 16, v71
	v_and_b32_e32 v127, 0xffff0000, v71
	v_pk_mul_f32 v[130:131], v[112:113], v[112:113]
	v_pk_fma_f32 v[130:131], v[114:115], v[114:115], v[130:131]
	v_pk_fma_f32 v[130:131], v[116:117], v[116:117], v[130:131]
	v_pk_fma_f32 v[130:131], v[118:119], v[118:119], v[130:131]
	v_pk_fma_f32 v[130:131], v[120:121], v[120:121], v[130:131]
	v_pk_fma_f32 v[130:131], v[122:123], v[122:123], v[130:131]
	v_pk_fma_f32 v[130:131], v[124:125], v[124:125], v[130:131]
	v_pk_fma_f32 v[130:131], v[126:127], v[126:127], v[130:131]
	s_nop 0
	v_add_f32_e32 v130, v130, v131
	s_nop 1
	v_add_f32_dpp v128, v128, v128 quad_perm:[1,0,3,2] row_mask:0xf bank_mask:0xf
	v_add_f32_dpp v130, v130, v130 quad_perm:[1,0,3,2] row_mask:0xf bank_mask:0xf
	s_nop 0
	v_add_f32_dpp v128, v128, v128 quad_perm:[2,3,0,1] row_mask:0xf bank_mask:0xf
	v_add_f32_dpp v130, v130, v130 quad_perm:[2,3,0,1] row_mask:0xf bank_mask:0xf
	s_nop 0
	v_add_f32_dpp v128, v128, v128 row_half_mirror row_mask:0xf bank_mask:0xf
	v_add_f32_dpp v130, v130, v130 row_half_mirror row_mask:0xf bank_mask:0xf
	s_nop 0
	v_add_f32_dpp v128, v128, v128 row_mirror row_mask:0xf bank_mask:0xf
	v_add_f32_dpp v130, v130, v130 row_mirror row_mask:0xf bank_mask:0xf
	s_nop 0
	ds_bpermute_b32 v136, v187, v128
	ds_bpermute_b32 v137, v187, v130
	s_waitcnt lgkmcnt(0)
;     __device__ __forceinline__ float* out() const { return (float*)karg_in(33); }
; __device__ __forceinline__ float ssq4(v4f v) { return (v.x * v.x + v.y * v.y) + (v.z * v.z + v.w * v.w); }
; template <int R, bool BASE_F32, bool OUT_F32>
; __device__ __forceinline__ void rows_res(const Ctx& C, int m0, int stride, int mx, const float* gpost, float scale, int lane) {
;     ...
;     for (int r = 0; r < R; ++r) { float s = 0.f;
; #pragma unroll
;         for (int j = 0; j < 4; ++j) s += ssq4(d[r][j]);
;         r1[r] = s; }
; #pragma unroll
;     for (int r = 0; r < R; ++r) r1[r] = rsqrtf(wave_sum(r1[r]) * (1.f / DM) + EPS) * scale;
; #pragma unroll
;     for (int j = 0; j < 4; ++j) { const v4f gp = ld4_f32(gpost + 4 * lane + 256 * j);
; #pragma unroll
;         for (int r = 0; r < R; ++r) d[r][j] = b[r][j] + d[r][j] * r1[r] * gp; }
;     if (OUT_F32) { float* Y = C.out();
; #pragma unroll
;         for (int r = 0; r < R; ++r)
; #pragma unroll
;             for (int j = 0; j < 4; ++j) if (ok[r]) *(v4f*)(Y + (size_t)mr[r] * DM + 4 * lane + 256 * j) = d[r][j];
	v_add_f32_e32 v128, v128, v136
	v_add_f32_e32 v130, v130, v137
	ds_bpermute_b32 v136, v188, v128
	ds_bpermute_b32 v137, v188, v130
	s_waitcnt lgkmcnt(0)
	v_add_f32_e32 v128, v128, v136
	v_add_f32_e32 v130, v130, v137
	v_fmamk_f32 v128, v128, 0x3a800000, v138
	v_fmamk_f32 v130, v130, 0x3a800000, v138
	s_nop 0
	v_rsq_f32_e32 v128, v128
	v_rsq_f32_e32 v130, v130
	s_nop 1
	v_mul_f32_e32 v128, 0.5, v128
	v_mul_f32_e32 v130, 0.5, v130
	s_waitcnt vmcnt(26)
	v_pk_mul_f32 v[96:97], v[128:129], v[96:97] op_sel_hi:[0,1]
	v_pk_mul_f32 v[98:99], v[128:129], v[98:99] op_sel_hi:[0,1]
	v_pk_mul_f32 v[100:101], v[128:129], v[100:101] op_sel_hi:[0,1]
	v_pk_mul_f32 v[102:103], v[128:129], v[102:103] op_sel_hi:[0,1]
	v_pk_mul_f32 v[104:105], v[128:129], v[104:105] op_sel_hi:[0,1]
	v_pk_mul_f32 v[106:107], v[128:129], v[106:107] op_sel_hi:[0,1]
	v_pk_mul_f32 v[108:109], v[128:129], v[108:109] op_sel_hi:[0,1]
	v_pk_mul_f32 v[110:111], v[128:129], v[110:111] op_sel_hi:[0,1]
	v_pk_mul_f32 v[96:97], v[96:97], v[192:193]
	v_pk_mul_f32 v[98:99], v[98:99], v[194:195]
	v_pk_mul_f32 v[100:101], v[100:101], v[196:197]
	v_pk_mul_f32 v[102:103], v[102:103], v[198:199]
	v_pk_mul_f32 v[104:105], v[104:105], v[200:201]
	v_pk_mul_f32 v[106:107], v[106:107], v[202:203]
	v_pk_mul_f32 v[108:109], v[108:109], v[204:205]
	v_pk_mul_f32 v[110:111], v[110:111], v[206:207]
	v_lshlrev_b32_e32 v56, 16, v72
	v_and_b32_e32 v57, 0xffff0000, v72
	v_lshlrev_b32_e32 v58, 16, v73
	v_and_b32_e32 v59, 0xffff0000, v73
	v_lshlrev_b32_e32 v60, 16, v74
	v_and_b32_e32 v61, 0xffff0000, v74
	v_lshlrev_b32_e32 v62, 16, v75
	v_and_b32_e32 v63, 0xffff0000, v75
	v_pk_fma_f32 v[96:97], v[88:89], v[56:57], v[96:97] op_sel_hi:[0,1,1]
	v_pk_fma_f32 v[98:99], v[88:89], v[58:59], v[98:99] op_sel_hi:[0,1,1]
	v_pk_fma_f32 v[100:101], v[88:89], v[60:61], v[100:101] op_sel_hi:[0,1,1]
	v_pk_fma_f32 v[102:103], v[88:89], v[62:63], v[102:103] op_sel_hi:[0,1,1]
	v_lshlrev_b32_e32 v56, 16, v76
	v_and_b32_e32 v57, 0xffff0000, v76
	v_lshlrev_b32_e32 v58, 16, v77
	v_and_b32_e32 v59, 0xffff0000, v77
	v_lshlrev_b32_e32 v60, 16, v78
	v_and_b32_e32 v61, 0xffff0000, v78
	v_lshlrev_b32_e32 v62, 16, v79
	v_and_b32_e32 v63, 0xffff0000, v79
	v_pk_fma_f32 v[104:105], v[88:89], v[56:57], v[104:105] op_sel_hi:[0,1,1]
	v_pk_fma_f32 v[106:107], v[88:89], v[58:59], v[106:107] op_sel_hi:[0,1,1]
	v_pk_fma_f32 v[108:109], v[88:89], v[60:61], v[108:109] op_sel_hi:[0,1,1]
	v_pk_fma_f32 v[110:111], v[88:89], v[62:63], v[110:111] op_sel_hi:[0,1,1]
	global_store_dwordx4 v175, v[96:99], s[100:101] nt
	global_store_dwordx4 v175, v[100:103], s[100:101] offset:1024 nt
	global_store_dwordx4 v175, v[104:107], s[100:101] offset:2048 nt
	global_store_dwordx4 v175, v[108:111], s[100:101] offset:3072 nt
	v_add_u32_e32 v175, 0x800000, v175
	v_pk_mul_f32 v[112:113], v[130:131], v[112:113] op_sel_hi:[0,1]
	v_pk_mul_f32 v[114:115], v[130:131], v[114:115] op_sel_hi:[0,1]
	v_pk_mul_f32 v[116:117], v[130:131], v[116:117] op_sel_hi:[0,1]
	v_pk_mul_f32 v[118:119], v[130:131], v[118:119] op_sel_hi:[0,1]
	v_pk_mul_f32 v[120:121], v[130:131], v[120:121] op_sel_hi:[0,1]
	v_pk_mul_f32 v[122:123], v[130:131], v[122:123] op_sel_hi:[0,1]
	v_pk_mul_f32 v[124:125], v[130:131], v[124:125] op_sel_hi:[0,1]
	v_pk_mul_f32 v[126:127], v[130:131], v[126:127] op_sel_hi:[0,1]
	v_pk_mul_f32 v[112:113], v[112:113], v[192:193]
	v_pk_mul_f32 v[114:115], v[114:115], v[194:195]
	v_pk_mul_f32 v[116:117], v[116:117], v[196:197]
	v_pk_mul_f32 v[118:119], v[118:119], v[198:199]
	v_pk_mul_f32 v[120:121], v[120:121], v[200:201]
	v_pk_mul_f32 v[122:123], v[122:123], v[202:203]
	v_pk_mul_f32 v[124:125], v[124:125], v[204:205]
	v_pk_mul_f32 v[126:127], v[126:127], v[206:207]
	v_lshlrev_b32_e32 v64, 16, v80
	v_and_b32_e32 v65, 0xffff0000, v80
	v_lshlrev_b32_e32 v66, 16, v81
	v_and_b32_e32 v67, 0xffff0000, v81
	v_lshlrev_b32_e32 v68, 16, v82
	v_and_b32_e32 v69, 0xffff0000, v82
	v_lshlrev_b32_e32 v70, 16, v83
	v_and_b32_e32 v71, 0xffff0000, v83
	v_pk_fma_f32 v[112:113], v[90:91], v[64:65], v[112:113] op_sel_hi:[0,1,1]
	v_pk_fma_f32 v[114:115], v[90:91], v[66:67], v[114:115] op_sel_hi:[0,1,1]
	v_pk_fma_f32 v[116:117], v[90:91], v[68:69], v[116:117] op_sel_hi:[0,1,1]
	v_pk_fma_f32 v[118:119], v[90:91], v[70:71], v[118:119] op_sel_hi:[0,1,1]
	v_lshlrev_b32_e32 v64, 16, v84
	v_and_b32_e32 v65, 0xffff0000, v84
	v_lshlrev_b32_e32 v66, 16, v85
	v_and_b32_e32 v67, 0xffff0000, v85
	v_lshlrev_b32_e32 v68, 16, v86
	v_and_b32_e32 v69, 0xffff0000, v86
	v_lshlrev_b32_e32 v70, 16, v87
	v_and_b32_e32 v71, 0xffff0000, v87
	v_pk_fma_f32 v[120:121], v[90:91], v[64:65], v[120:121] op_sel_hi:[0,1,1]
	v_pk_fma_f32 v[122:123], v[90:91], v[66:67], v[122:123] op_sel_hi:[0,1,1]
	v_pk_fma_f32 v[124:125], v[90:91], v[68:69], v[124:125] op_sel_hi:[0,1,1]
	v_pk_fma_f32 v[126:127], v[90:91], v[70:71], v[126:127] op_sel_hi:[0,1,1]
	global_store_dwordx4 v175, v[112:115], s[100:101] nt
	global_store_dwordx4 v175, v[116:119], s[100:101] offset:1024 nt
	global_store_dwordx4 v175, v[120:123], s[100:101] offset:2048 nt
	global_store_dwordx4 v175, v[124:127], s[100:101] offset:3072 nt
	v_add_u32_e32 v175, 0x800000, v175
	global_load_dword v88, v172, s[98:99]
	global_load_dwordx2 v[56:57], v170, s[98:99]
	global_load_dwordx2 v[58:59], v170, s[98:99] offset:512
	global_load_dwordx2 v[60:61], v170, s[98:99] offset:1024
	global_load_dwordx2 v[62:63], v170, s[98:99] offset:1536
	global_load_dwordx2 v[72:73], v171, s[98:99]
	global_load_dwordx2 v[74:75], v171, s[98:99] offset:512
	global_load_dwordx2 v[76:77], v171, s[98:99] offset:1024
	global_load_dwordx2 v[78:79], v171, s[98:99] offset:1536
	v_add_u32_e32 v170, 0x400000, v170
	v_add_u32_e32 v171, 0x400000, v171
	v_add_u32_e32 v172, 0x2000, v172
	global_load_dword v90, v172, s[98:99]
	global_load_dwordx2 v[64:65], v170, s[98:99]
	global_load_dwordx2 v[66:67], v170, s[98:99] offset:512
	global_load_dwordx2 v[68:69], v170, s[98:99] offset:1024
	global_load_dwordx2 v[70:71], v170, s[98:99] offset:1536
	global_load_dwordx2 v[80:81], v171, s[98:99]
	global_load_dwordx2 v[82:83], v171, s[98:99] offset:512
	global_load_dwordx2 v[84:85], v171, s[98:99] offset:1024
	global_load_dwordx2 v[86:87], v171, s[98:99] offset:1536
	v_add_u32_e32 v170, 0x400000, v170
	v_add_u32_e32 v171, 0x400000, v171
	v_add_u32_e32 v172, 0x2000, v172
	s_waitcnt vmcnt(39)
;     __device__ __forceinline__ float* out() const { return (float*)karg_in(33); }
; __device__ __forceinline__ float ssq4(v4f v) { return (v.x * v.x + v.y * v.y) + (v.z * v.z + v.w * v.w); }
; template <int R, bool BASE_F32, bool OUT_F32>
; __device__ __forceinline__ void rows_res(const Ctx& C, int m0, int stride, int mx, const float* gpost, float scale, int lane) {
;     ...
;     for (int r = 0; r < R; ++r) { float s = 0.f;
; #pragma unroll
;         for (int j = 0; j < 4; ++j) s += ssq4(d[r][j]);
;         r1[r] = s; }
; #pragma unroll
;     for (int r = 0; r < R; ++r) r1[r] = rsqrtf(wave_sum(r1[r]) * (1.f / DM) + EPS) * scale;
; #pragma unroll
;     for (int j = 0; j < 4; ++j) { const v4f gp = ld4_f32(gpost + 4 * lane + 256 * j);
; #pragma unroll
;         for (int r = 0; r < R; ++r) d[r][j] = b[r][j] + d[r][j] * r1[r] * gp; }
;     if (OUT_F32) { float* Y = C.out();
; #pragma unroll
;         for (int r = 0; r < R; ++r)
; #pragma unroll
;             for (int j = 0; j < 4; ++j) if (ok[r]) *(v4f*)(Y + (size_t)mr[r] * DM + 4 * lane + 256 * j) = d[r][j];
	v_lshlrev_b32_e32 v96, 16, v20
	v_and_b32_e32 v97, 0xffff0000, v20
	v_lshlrev_b32_e32 v98, 16, v21
	v_and_b32_e32 v99, 0xffff0000, v21
	v_lshlrev_b32_e32 v100, 16, v22
	v_and_b32_e32 v101, 0xffff0000, v22
	v_lshlrev_b32_e32 v102, 16, v23
	v_and_b32_e32 v103, 0xffff0000, v23
	v_lshlrev_b32_e32 v104, 16, v24
	v_and_b32_e32 v105, 0xffff0000, v24
	v_lshlrev_b32_e32 v106, 16, v25
	v_and_b32_e32 v107, 0xffff0000, v25
	v_lshlrev_b32_e32 v108, 16, v26
	v_and_b32_e32 v109, 0xffff0000, v26
	v_lshlrev_b32_e32 v110, 16, v27
	v_and_b32_e32 v111, 0xffff0000, v27
	v_pk_mul_f32 v[128:129], v[96:97], v[96:97]
	v_pk_fma_f32 v[128:129], v[98:99], v[98:99], v[128:129]
	v_pk_fma_f32 v[128:129], v[100:101], v[100:101], v[128:129]
	v_pk_fma_f32 v[128:129], v[102:103], v[102:103], v[128:129]
	v_pk_fma_f32 v[128:129], v[104:105], v[104:105], v[128:129]
	v_pk_fma_f32 v[128:129], v[106:107], v[106:107], v[128:129]
	v_pk_fma_f32 v[128:129], v[108:109], v[108:109], v[128:129]
	v_pk_fma_f32 v[128:129], v[110:111], v[110:111], v[128:129]
	s_nop 0
	v_add_f32_e32 v128, v128, v129
	s_waitcnt vmcnt(30)
	v_lshlrev_b32_e32 v112, 16, v28
	v_and_b32_e32 v113, 0xffff0000, v28
	v_lshlrev_b32_e32 v114, 16, v29
	v_and_b32_e32 v115, 0xffff0000, v29
	v_lshlrev_b32_e32 v116, 16, v30
	v_and_b32_e32 v117, 0xffff0000, v30
	v_lshlrev_b32_e32 v118, 16, v31
	v_and_b32_e32 v119, 0xffff0000, v31
	v_lshlrev_b32_e32 v120, 16, v32
	v_and_b32_e32 v121, 0xffff0000, v32
	v_lshlrev_b32_e32 v122, 16, v33
	v_and_b32_e32 v123, 0xffff0000, v33
	v_lshlrev_b32_e32 v124, 16, v34
	v_and_b32_e32 v125, 0xffff0000, v34
	v_lshlrev_b32_e32 v126, 16, v35
	v_and_b32_e32 v127, 0xffff0000, v35
	v_pk_mul_f32 v[130:131], v[112:113], v[112:113]
	v_pk_fma_f32 v[130:131], v[114:115], v[114:115], v[130:131]
	v_pk_fma_f32 v[130:131], v[116:117], v[116:117], v[130:131]
	v_pk_fma_f32 v[130:131], v[118:119], v[118:119], v[130:131]
	v_pk_fma_f32 v[130:131], v[120:121], v[120:121], v[130:131]
	v_pk_fma_f32 v[130:131], v[122:123], v[122:123], v[130:131]
	v_pk_fma_f32 v[130:131], v[124:125], v[124:125], v[130:131]
	v_pk_fma_f32 v[130:131], v[126:127], v[126:127], v[130:131]
	s_nop 0
	v_add_f32_e32 v130, v130, v131
	s_nop 1
	v_add_f32_dpp v128, v128, v128 quad_perm:[1,0,3,2] row_mask:0xf bank_mask:0xf
	v_add_f32_dpp v130, v130, v130 quad_perm:[1,0,3,2] row_mask:0xf bank_mask:0xf
	s_nop 0
	v_add_f32_dpp v128, v128, v128 quad_perm:[2,3,0,1] row_mask:0xf bank_mask:0xf
	v_add_f32_dpp v130, v130, v130 quad_perm:[2,3,0,1] row_mask:0xf bank_mask:0xf
	s_nop 0
	v_add_f32_dpp v128, v128, v128 row_half_mirror row_mask:0xf bank_mask:0xf
	v_add_f32_dpp v130, v130, v130 row_half_mirror row_mask:0xf bank_mask:0xf
	s_nop 0
	v_add_f32_dpp v128, v128, v128 row_mirror row_mask:0xf bank_mask:0xf
	v_add_f32_dpp v130, v130, v130 row_mirror row_mask:0xf bank_mask:0xf
	s_nop 0
	ds_bpermute_b32 v136, v187, v128
	ds_bpermute_b32 v137, v187, v130
	s_waitcnt lgkmcnt(0)
	v_add_f32_e32 v128, v128, v136
	v_add_f32_e32 v130, v130, v137
	ds_bpermute_b32 v136, v188, v128
	ds_bpermute_b32 v137, v188, v130
	s_waitcnt lgkmcnt(0)
	v_add_f32_e32 v128, v128, v136
	v_add_f32_e32 v130, v130, v137
	v_fmamk_f32 v128, v128, 0x3a800000, v138
	v_fmamk_f32 v130, v130, 0x3a800000, v138
	s_nop 0
	v_rsq_f32_e32 v128, v128
	v_rsq_f32_e32 v130, v130
	s_nop 1
	v_mul_f32_e32 v128, 0.5, v128
	v_mul_f32_e32 v130, 0.5, v130
	s_waitcnt vmcnt(26)
	v_pk_mul_f32 v[96:97], v[128:129], v[96:97] op_sel_hi:[0,1]
	v_pk_mul_f32 v[98:99], v[128:129], v[98:99] op_sel_hi:[0,1]
	v_pk_mul_f32 v[100:101], v[128:129], v[100:101] op_sel_hi:[0,1]
	v_pk_mul_f32 v[102:103], v[128:129], v[102:103] op_sel_hi:[0,1]
	v_pk_mul_f32 v[104:105], v[128:129], v[104:105] op_sel_hi:[0,1]
	v_pk_mul_f32 v[106:107], v[128:129], v[106:107] op_sel_hi:[0,1]
	v_pk_mul_f32 v[108:109], v[128:129], v[108:109] op_sel_hi:[0,1]
	v_pk_mul_f32 v[110:111], v[128:129], v[110:111] op_sel_hi:[0,1]
	v_pk_mul_f32 v[96:97], v[96:97], v[192:193]
	v_pk_mul_f32 v[98:99], v[98:99], v[194:195]
	v_pk_mul_f32 v[100:101], v[100:101], v[196:197]
	v_pk_mul_f32 v[102:103], v[102:103], v[198:199]
	v_pk_mul_f32 v[104:105], v[104:105], v[200:201]
	v_pk_mul_f32 v[106:107], v[106:107], v[202:203]
	v_pk_mul_f32 v[108:109], v[108:109], v[204:205]
	v_pk_mul_f32 v[110:111], v[110:111], v[206:207]
	v_lshlrev_b32_e32 v20, 16, v36
	v_and_b32_e32 v21, 0xffff0000, v36
	v_lshlrev_b32_e32 v22, 16, v37
	v_and_b32_e32 v23, 0xffff0000, v37
	v_lshlrev_b32_e32 v24, 16, v38
	v_and_b32_e32 v25, 0xffff0000, v38
	v_lshlrev_b32_e32 v26, 16, v39
	v_and_b32_e32 v27, 0xffff0000, v39
	v_pk_fma_f32 v[96:97], v[52:53], v[20:21], v[96:97] op_sel_hi:[0,1,1]
	v_pk_fma_f32 v[98:99], v[52:53], v[22:23], v[98:99] op_sel_hi:[0,1,1]
	v_pk_fma_f32 v[100:101], v[52:53], v[24:25], v[100:101] op_sel_hi:[0,1,1]
	v_pk_fma_f32 v[102:103], v[52:53], v[26:27], v[102:103] op_sel_hi:[0,1,1]
	v_lshlrev_b32_e32 v20, 16, v40
	v_and_b32_e32 v21, 0xffff0000, v40
	v_lshlrev_b32_e32 v22, 16, v41
	v_and_b32_e32 v23, 0xffff0000, v41
	v_lshlrev_b32_e32 v24, 16, v42
	v_and_b32_e32 v25, 0xffff0000, v42
	v_lshlrev_b32_e32 v26, 16, v43
	v_and_b32_e32 v27, 0xffff0000, v43
	v_pk_fma_f32 v[104:105], v[52:53], v[20:21], v[104:105] op_sel_hi:[0,1,1]
	v_pk_fma_f32 v[106:107], v[52:53], v[22:23], v[106:107] op_sel_hi:[0,1,1]
	v_pk_fma_f32 v[108:109], v[52:53], v[24:25], v[108:109] op_sel_hi:[0,1,1]
	v_pk_fma_f32 v[110:111], v[52:53], v[26:27], v[110:111] op_sel_hi:[0,1,1]
	global_store_dwordx4 v175, v[96:99], s[100:101] nt
	global_store_dwordx4 v175, v[100:103], s[100:101] offset:1024 nt
	global_store_dwordx4 v175, v[104:107], s[100:101] offset:2048 nt
	global_store_dwordx4 v175, v[108:111], s[100:101] offset:3072 nt
;     __device__ __forceinline__ float* out() const { return (float*)karg_in(33); }
; __device__ __forceinline__ float ssq4(v4f v) { return (v.x * v.x + v.y * v.y) + (v.z * v.z + v.w * v.w); }
; template <int R, bool BASE_F32, bool OUT_F32>
; __device__ __forceinline__ void rows_res(const Ctx& C, int m0, int stride, int mx, const float* gpost, float scale, int lane) {
;     ...
;     for (int r = 0; r < R; ++r) { float s = 0.f;
; #pragma unroll
;         for (int j = 0; j < 4; ++j) s += ssq4(d[r][j]);
;         r1[r] = s; }
; #pragma unroll
;     for (int r = 0; r < R; ++r) r1[r] = rsqrtf(wave_sum(r1[r]) * (1.f / DM) + EPS) * scale;
; #pragma unroll
;     for (int j = 0; j < 4; ++j) { const v4f gp = ld4_f32(gpost + 4 * lane + 256 * j);
; #pragma unroll
;         for (int r = 0; r < R; ++r) d[r][j] = b[r][j] + d[r][j] * r1[r] * gp; }
;     if (OUT_F32) { float* Y = C.out();
; #pragma unroll
;         for (int r = 0; r < R; ++r)
; #pragma unroll
;             for (int j = 0; j < 4; ++j) if (ok[r]) *(v4f*)(Y + (size_t)mr[r] * DM + 4 * lane + 256 * j) = d[r][j];
	v_add_u32_e32 v175, 0x800000, v175
	v_pk_mul_f32 v[112:113], v[130:131], v[112:113] op_sel_hi:[0,1]
	v_pk_mul_f32 v[114:115], v[130:131], v[114:115] op_sel_hi:[0,1]
	v_pk_mul_f32 v[116:117], v[130:131], v[116:117] op_sel_hi:[0,1]
	v_pk_mul_f32 v[118:119], v[130:131], v[118:119] op_sel_hi:[0,1]
	v_pk_mul_f32 v[120:121], v[130:131], v[120:121] op_sel_hi:[0,1]
	v_pk_mul_f32 v[122:123], v[130:131], v[122:123] op_sel_hi:[0,1]
	v_pk_mul_f32 v[124:125], v[130:131], v[124:125] op_sel_hi:[0,1]
	v_pk_mul_f32 v[126:127], v[130:131], v[126:127] op_sel_hi:[0,1]
	v_pk_mul_f32 v[112:113], v[112:113], v[192:193]
	v_pk_mul_f32 v[114:115], v[114:115], v[194:195]
	v_pk_mul_f32 v[116:117], v[116:117], v[196:197]
	v_pk_mul_f32 v[118:119], v[118:119], v[198:199]
	v_pk_mul_f32 v[120:121], v[120:121], v[200:201]
	v_pk_mul_f32 v[122:123], v[122:123], v[202:203]
	v_pk_mul_f32 v[124:125], v[124:125], v[204:205]
	v_pk_mul_f32 v[126:127], v[126:127], v[206:207]
	v_lshlrev_b32_e32 v28, 16, v44
	v_and_b32_e32 v29, 0xffff0000, v44
	v_lshlrev_b32_e32 v30, 16, v45
	v_and_b32_e32 v31, 0xffff0000, v45
	v_lshlrev_b32_e32 v32, 16, v46
	v_and_b32_e32 v33, 0xffff0000, v46
	v_lshlrev_b32_e32 v34, 16, v47
	v_and_b32_e32 v35, 0xffff0000, v47
	v_pk_fma_f32 v[112:113], v[54:55], v[28:29], v[112:113] op_sel_hi:[0,1,1]
	v_pk_fma_f32 v[114:115], v[54:55], v[30:31], v[114:115] op_sel_hi:[0,1,1]
	v_pk_fma_f32 v[116:117], v[54:55], v[32:33], v[116:117] op_sel_hi:[0,1,1]
	v_pk_fma_f32 v[118:119], v[54:55], v[34:35], v[118:119] op_sel_hi:[0,1,1]
	v_lshlrev_b32_e32 v28, 16, v48
	v_and_b32_e32 v29, 0xffff0000, v48
	v_lshlrev_b32_e32 v30, 16, v49
	v_and_b32_e32 v31, 0xffff0000, v49
	v_lshlrev_b32_e32 v32, 16, v50
	v_and_b32_e32 v33, 0xffff0000, v50
	v_lshlrev_b32_e32 v34, 16, v51
	v_and_b32_e32 v35, 0xffff0000, v51
	v_pk_fma_f32 v[120:121], v[54:55], v[28:29], v[120:121] op_sel_hi:[0,1,1]
	v_pk_fma_f32 v[122:123], v[54:55], v[30:31], v[122:123] op_sel_hi:[0,1,1]
	v_pk_fma_f32 v[124:125], v[54:55], v[32:33], v[124:125] op_sel_hi:[0,1,1]
	v_pk_fma_f32 v[126:127], v[54:55], v[34:35], v[126:127] op_sel_hi:[0,1,1]
	global_store_dwordx4 v175, v[112:115], s[100:101] nt
	global_store_dwordx4 v175, v[116:119], s[100:101] offset:1024 nt
	global_store_dwordx4 v175, v[120:123], s[100:101] offset:2048 nt
	global_store_dwordx4 v175, v[124:127], s[100:101] offset:3072 nt
	v_add_u32_e32 v175, 0x800000, v175
	s_waitcnt vmcnt(21)
	v_lshlrev_b32_e32 v96, 16, v56
	v_and_b32_e32 v97, 0xffff0000, v56
	v_lshlrev_b32_e32 v98, 16, v57
	v_and_b32_e32 v99, 0xffff0000, v57
	v_lshlrev_b32_e32 v100, 16, v58
	v_and_b32_e32 v101, 0xffff0000, v58
	v_lshlrev_b32_e32 v102, 16, v59
	v_and_b32_e32 v103, 0xffff0000, v59
	v_lshlrev_b32_e32 v104, 16, v60
	v_and_b32_e32 v105, 0xffff0000, v60
	v_lshlrev_b32_e32 v106, 16, v61
	v_and_b32_e32 v107, 0xffff0000, v61
	v_lshlrev_b32_e32 v108, 16, v62
	v_and_b32_e32 v109, 0xffff0000, v62
	v_lshlrev_b32_e32 v110, 16, v63
	v_and_b32_e32 v111, 0xffff0000, v63
	v_pk_mul_f32 v[128:129], v[96:97], v[96:97]
	v_pk_fma_f32 v[128:129], v[98:99], v[98:99], v[128:129]
	v_pk_fma_f32 v[128:129], v[100:101], v[100:101], v[128:129]
	v_pk_fma_f32 v[128:129], v[102:103], v[102:103], v[128:129]
	v_pk_fma_f32 v[128:129], v[104:105], v[104:105], v[128:129]
	v_pk_fma_f32 v[128:129], v[106:107], v[106:107], v[128:129]
	v_pk_fma_f32 v[128:129], v[108:109], v[108:109], v[128:129]
	v_pk_fma_f32 v[128:129], v[110:111], v[110:111], v[128:129]
	s_nop 0
	v_add_f32_e32 v128, v128, v129
	s_waitcnt vmcnt(12)
	v_lshlrev_b32_e32 v112, 16, v64
	v_and_b32_e32 v113, 0xffff0000, v64
	v_lshlrev_b32_e32 v114, 16, v65
	v_and_b32_e32 v115, 0xffff0000, v65
	v_lshlrev_b32_e32 v116, 16, v66
	v_and_b32_e32 v117, 0xffff0000, v66
	v_lshlrev_b32_e32 v118, 16, v67
	v_and_b32_e32 v119, 0xffff0000, v67
	v_lshlrev_b32_e32 v120, 16, v68
	v_and_b32_e32 v121, 0xffff0000, v68
	v_lshlrev_b32_e32 v122, 16, v69
	v_and_b32_e32 v123, 0xffff0000, v69
	v_lshlrev_b32_e32 v124, 16, v70
	v_and_b32_e32 v125, 0xffff0000, v70
	v_lshlrev_b32_e32 v126, 16, v71
	v_and_b32_e32 v127, 0xffff0000, v71
	v_pk_mul_f32 v[130:131], v[112:113], v[112:113]
	v_pk_fma_f32 v[130:131], v[114:115], v[114:115], v[130:131]
	v_pk_fma_f32 v[130:131], v[116:117], v[116:117], v[130:131]
	v_pk_fma_f32 v[130:131], v[118:119], v[118:119], v[130:131]
	v_pk_fma_f32 v[130:131], v[120:121], v[120:121], v[130:131]
	v_pk_fma_f32 v[130:131], v[122:123], v[122:123], v[130:131]
	v_pk_fma_f32 v[130:131], v[124:125], v[124:125], v[130:131]
	v_pk_fma_f32 v[130:131], v[126:127], v[126:127], v[130:131]
	s_nop 0
	v_add_f32_e32 v130, v130, v131
	s_nop 1
	v_add_f32_dpp v128, v128, v128 quad_perm:[1,0,3,2] row_mask:0xf bank_mask:0xf
	v_add_f32_dpp v130, v130, v130 quad_perm:[1,0,3,2] row_mask:0xf bank_mask:0xf
	s_nop 0
	v_add_f32_dpp v128, v128, v128 quad_perm:[2,3,0,1] row_mask:0xf bank_mask:0xf
	v_add_f32_dpp v130, v130, v130 quad_perm:[2,3,0,1] row_mask:0xf bank_mask:0xf
	s_nop 0
	v_add_f32_dpp v128, v128, v128 row_half_mirror row_mask:0xf bank_mask:0xf
	v_add_f32_dpp v130, v130, v130 row_half_mirror row_mask:0xf bank_mask:0xf
	s_nop 0
	v_add_f32_dpp v128, v128, v128 row_mirror row_mask:0xf bank_mask:0xf
	v_add_f32_dpp v130, v130, v130 row_mirror row_mask:0xf bank_mask:0xf
	s_nop 0
	ds_bpermute_b32 v136, v187, v128
	ds_bpermute_b32 v137, v187, v130
	s_waitcnt lgkmcnt(0)
;     __device__ __forceinline__ float* out() const { return (float*)karg_in(33); }
; __device__ __forceinline__ float ssq4(v4f v) { return (v.x * v.x + v.y * v.y) + (v.z * v.z + v.w * v.w); }
; template <int R, bool BASE_F32, bool OUT_F32>
; __device__ __forceinline__ void rows_res(const Ctx& C, int m0, int stride, int mx, const float* gpost, float scale, int lane) {
;     ...
;     for (int r = 0; r < R; ++r) { float s = 0.f;
; #pragma unroll
;         for (int j = 0; j < 4; ++j) s += ssq4(d[r][j]);
;         r1[r] = s; }
; #pragma unroll
;     for (int r = 0; r < R; ++r) r1[r] = rsqrtf(wave_sum(r1[r]) * (1.f / DM) + EPS) * scale;
; #pragma unroll
;     for (int j = 0; j < 4; ++j) { const v4f gp = ld4_f32(gpost + 4 * lane + 256 * j);
; #pragma unroll
;         for (int r = 0; r < R; ++r) d[r][j] = b[r][j] + d[r][j] * r1[r] * gp; }
;     if (OUT_F32) { float* Y = C.out();
; #pragma unroll
;         for (int r = 0; r < R; ++r)
; #pragma unroll
;             for (int j = 0; j < 4; ++j) if (ok[r]) *(v4f*)(Y + (size_t)mr[r] * DM + 4 * lane + 256 * j) = d[r][j];
	v_add_f32_e32 v128, v128, v136
	v_add_f32_e32 v130, v130, v137
	ds_bpermute_b32 v136, v188, v128
	ds_bpermute_b32 v137, v188, v130
	s_waitcnt lgkmcnt(0)
	v_add_f32_e32 v128, v128, v136
	v_add_f32_e32 v130, v130, v137
	v_fmamk_f32 v128, v128, 0x3a800000, v138
	v_fmamk_f32 v130, v130, 0x3a800000, v138
	s_nop 0
	v_rsq_f32_e32 v128, v128
	v_rsq_f32_e32 v130, v130
	s_nop 1
	v_mul_f32_e32 v128, 0.5, v128
	v_mul_f32_e32 v130, 0.5, v130
	s_waitcnt vmcnt(8)
	v_pk_mul_f32 v[96:97], v[128:129], v[96:97] op_sel_hi:[0,1]
	v_pk_mul_f32 v[98:99], v[128:129], v[98:99] op_sel_hi:[0,1]
	v_pk_mul_f32 v[100:101], v[128:129], v[100:101] op_sel_hi:[0,1]
	v_pk_mul_f32 v[102:103], v[128:129], v[102:103] op_sel_hi:[0,1]
	v_pk_mul_f32 v[104:105], v[128:129], v[104:105] op_sel_hi:[0,1]
	v_pk_mul_f32 v[106:107], v[128:129], v[106:107] op_sel_hi:[0,1]
	v_pk_mul_f32 v[108:109], v[128:129], v[108:109] op_sel_hi:[0,1]
	v_pk_mul_f32 v[110:111], v[128:129], v[110:111] op_sel_hi:[0,1]
	v_pk_mul_f32 v[96:97], v[96:97], v[192:193]
	v_pk_mul_f32 v[98:99], v[98:99], v[194:195]
	v_pk_mul_f32 v[100:101], v[100:101], v[196:197]
	v_pk_mul_f32 v[102:103], v[102:103], v[198:199]
	v_pk_mul_f32 v[104:105], v[104:105], v[200:201]
	v_pk_mul_f32 v[106:107], v[106:107], v[202:203]
	v_pk_mul_f32 v[108:109], v[108:109], v[204:205]
	v_pk_mul_f32 v[110:111], v[110:111], v[206:207]
	v_lshlrev_b32_e32 v56, 16, v72
	v_and_b32_e32 v57, 0xffff0000, v72
	v_lshlrev_b32_e32 v58, 16, v73
	v_and_b32_e32 v59, 0xffff0000, v73
	v_lshlrev_b32_e32 v60, 16, v74
	v_and_b32_e32 v61, 0xffff0000, v74
	v_lshlrev_b32_e32 v62, 16, v75
	v_and_b32_e32 v63, 0xffff0000, v75
	v_pk_fma_f32 v[96:97], v[88:89], v[56:57], v[96:97] op_sel_hi:[0,1,1]
	v_pk_fma_f32 v[98:99], v[88:89], v[58:59], v[98:99] op_sel_hi:[0,1,1]
	v_pk_fma_f32 v[100:101], v[88:89], v[60:61], v[100:101] op_sel_hi:[0,1,1]
	v_pk_fma_f32 v[102:103], v[88:89], v[62:63], v[102:103] op_sel_hi:[0,1,1]
	v_lshlrev_b32_e32 v56, 16, v76
	v_and_b32_e32 v57, 0xffff0000, v76
	v_lshlrev_b32_e32 v58, 16, v77
	v_and_b32_e32 v59, 0xffff0000, v77
	v_lshlrev_b32_e32 v60, 16, v78
	v_and_b32_e32 v61, 0xffff0000, v78
	v_lshlrev_b32_e32 v62, 16, v79
	v_and_b32_e32 v63, 0xffff0000, v79
	v_pk_fma_f32 v[104:105], v[88:89], v[56:57], v[104:105] op_sel_hi:[0,1,1]
	v_pk_fma_f32 v[106:107], v[88:89], v[58:59], v[106:107] op_sel_hi:[0,1,1]
	v_pk_fma_f32 v[108:109], v[88:89], v[60:61], v[108:109] op_sel_hi:[0,1,1]
	v_pk_fma_f32 v[110:111], v[88:89], v[62:63], v[110:111] op_sel_hi:[0,1,1]
	global_store_dwordx4 v175, v[96:99], s[100:101] nt
	global_store_dwordx4 v175, v[100:103], s[100:101] offset:1024 nt
	global_store_dwordx4 v175, v[104:107], s[100:101] offset:2048 nt
	global_store_dwordx4 v175, v[108:111], s[100:101] offset:3072 nt
	v_add_u32_e32 v175, 0x800000, v175
	v_pk_mul_f32 v[112:113], v[130:131], v[112:113] op_sel_hi:[0,1]
	v_pk_mul_f32 v[114:115], v[130:131], v[114:115] op_sel_hi:[0,1]
	v_pk_mul_f32 v[116:117], v[130:131], v[116:117] op_sel_hi:[0,1]
	v_pk_mul_f32 v[118:119], v[130:131], v[118:119] op_sel_hi:[0,1]
	v_pk_mul_f32 v[120:121], v[130:131], v[120:121] op_sel_hi:[0,1]
	v_pk_mul_f32 v[122:123], v[130:131], v[122:123] op_sel_hi:[0,1]
	v_pk_mul_f32 v[124:125], v[130:131], v[124:125] op_sel_hi:[0,1]
	v_pk_mul_f32 v[126:127], v[130:131], v[126:127] op_sel_hi:[0,1]
	v_pk_mul_f32 v[112:113], v[112:113], v[192:193]
	v_pk_mul_f32 v[114:115], v[114:115], v[194:195]
	v_pk_mul_f32 v[116:117], v[116:117], v[196:197]
	v_pk_mul_f32 v[118:119], v[118:119], v[198:199]
	v_pk_mul_f32 v[120:121], v[120:121], v[200:201]
	v_pk_mul_f32 v[122:123], v[122:123], v[202:203]
	v_pk_mul_f32 v[124:125], v[124:125], v[204:205]
	v_pk_mul_f32 v[126:127], v[126:127], v[206:207]
	v_lshlrev_b32_e32 v64, 16, v80
	v_and_b32_e32 v65, 0xffff0000, v80
	v_lshlrev_b32_e32 v66, 16, v81
	v_and_b32_e32 v67, 0xffff0000, v81
	v_lshlrev_b32_e32 v68, 16, v82
	v_and_b32_e32 v69, 0xffff0000, v82
	v_lshlrev_b32_e32 v70, 16, v83
	v_and_b32_e32 v71, 0xffff0000, v83
	v_pk_fma_f32 v[112:113], v[90:91], v[64:65], v[112:113] op_sel_hi:[0,1,1]
	v_pk_fma_f32 v[114:115], v[90:91], v[66:67], v[114:115] op_sel_hi:[0,1,1]
	v_pk_fma_f32 v[116:117], v[90:91], v[68:69], v[116:117] op_sel_hi:[0,1,1]
	v_pk_fma_f32 v[118:119], v[90:91], v[70:71], v[118:119] op_sel_hi:[0,1,1]
	v_lshlrev_b32_e32 v64, 16, v84
	v_and_b32_e32 v65, 0xffff0000, v84
	v_lshlrev_b32_e32 v66, 16, v85
	v_and_b32_e32 v67, 0xffff0000, v85
	v_lshlrev_b32_e32 v68, 16, v86
	v_and_b32_e32 v69, 0xffff0000, v86
	v_lshlrev_b32_e32 v70, 16, v87
	v_and_b32_e32 v71, 0xffff0000, v87
	v_pk_fma_f32 v[120:121], v[90:91], v[64:65], v[120:121] op_sel_hi:[0,1,1]
	v_pk_fma_f32 v[122:123], v[90:91], v[66:67], v[122:123] op_sel_hi:[0,1,1]
	v_pk_fma_f32 v[124:125], v[90:91], v[68:69], v[124:125] op_sel_hi:[0,1,1]
	v_pk_fma_f32 v[126:127], v[90:91], v[70:71], v[126:127] op_sel_hi:[0,1,1]
	global_store_dwordx4 v175, v[112:115], s[100:101] nt
	global_store_dwordx4 v175, v[116:119], s[100:101] offset:1024 nt
	global_store_dwordx4 v175, v[120:123], s[100:101] offset:2048 nt
	global_store_dwordx4 v175, v[124:127], s[100:101] offset:3072 nt
	v_add_u32_e32 v175, 0x800000, v175
	s_branch .LBB0_1283
	s_waitcnt lgkmcnt(0)
	v_lshl_add_u64 v[20:21], s[8:9], 0, v[16:17]
	v_mov_b32_e32 v19, v17
	s_mov_b64 s[10:11], 0x7100000
	s_mov_b64 s[12:13], 0x3000000
	v_mov_b32_e32 v23, 0x2a80000
	v_mov_b32_e32 v22, 0x358637bd
	s_mov_b32 s14, 0x3a800000
	s_mov_b32 s27, 0x800000
	s_mov_b32 s16, s15
	s_branch .LBB0_1275
